# pool unit epilogue stores widened the same way (v_permlane32_swap pairs, dwordx4)
# speedup vs baseline: 1.0264x; 1.0064x over previous
.Lpool_xdma_done0:
	v_readlane_b32 s54, v250, 23
	v_readlane_b32 s55, v250, 24
	v_mov_b32_e32 v2, v45
	v_mov_b32_e32 v3, 0
	s_add_i32 s43, s48, 0x1a000
	v_lshl_add_u64 v[4:5], s[54:55], 0, v[2:3]
	s_mov_b32 m0, s43
	s_nop 0
	global_load_lds_dwordx4 v[4:5], off
	v_and_b32_e32 v94, 32, v216
	v_lshrrev_b32_e32 v94, 2, v94
	v_mov_b32_e32 v95, 0
	v_lshl_add_u64 v[96:97], v[10:11], 0, v[94:95]
	v_lshl_add_u64 v[4:5], s[52:53], 0, v[10:11]
	global_load_dwordx2 v[12:13], v[4:5], off offset:0
	global_load_dwordx2 v[14:15], v[4:5], off offset:16
	global_load_dwordx2 v[16:17], v[4:5], off offset:32
	global_load_dwordx2 v[18:19], v[4:5], off offset:48
	global_load_dwordx2 v[20:21], v[4:5], off offset:64
	global_load_dwordx2 v[22:23], v[4:5], off offset:80
	global_load_dwordx2 v[24:25], v[4:5], off offset:96
	global_load_dwordx2 v[26:27], v[4:5], off offset:112
	s_waitcnt vmcnt(8)
	s_barrier
	s_add_u32 s46, s44, 0x80
	s_addc_u32 s47, s45, 0
	s_add_i32 s43, s48, 0x8800
	v_lshl_add_u64 v[4:5], s[46:47], 0, v[6:7]
	s_mov_b32 m0, s43
	s_nop 0
	global_load_lds_dwordx4 v[4:5], off
	s_add_u32 s46, s44, 0x8080
	s_addc_u32 s47, s45, 0
	s_add_i32 s43, s48, 0xa800
	v_lshl_add_u64 v[4:5], s[46:47], 0, v[6:7]
	s_mov_b32 m0, s43
	s_nop 0
	global_load_lds_dwordx4 v[4:5], off
	s_add_u32 s46, s44, 0x10080
	s_addc_u32 s47, s45, 0
	s_add_i32 s43, s48, 0xc800
	v_lshl_add_u64 v[4:5], s[46:47], 0, v[6:7]
	s_mov_b32 m0, s43
	s_nop 0
	global_load_lds_dwordx4 v[4:5], off
	s_add_u32 s46, s44, 0x18080
	s_addc_u32 s47, s45, 0
	s_add_i32 s43, s48, 0xe800
	v_lshl_add_u64 v[4:5], s[46:47], 0, v[6:7]
	s_mov_b32 m0, s43
	s_nop 0
	global_load_lds_dwordx4 v[4:5], off
	s_cmp_lt_u32 s41, 2
	s_cbranch_scc0 .Lpool_xdma_done1
	s_add_u32 s46, s44, 0x20080
	s_addc_u32 s47, s45, 0
	s_add_i32 s43, s48, 0x10800
	v_lshl_add_u64 v[4:5], s[46:47], 0, v[6:7]
	s_mov_b32 m0, s43
	s_nop 0
	global_load_lds_dwordx4 v[4:5], off

.Lpool_nz0:
	v_add_f32_e32 v93, v61, v60
	s_cmp_eq_u32 s42, 1
	s_cselect_b32 s51, 0x3f800000, s50
	v_fma_f32 v2, v93, s51, -v61
	v_add_f32_e32 v93, v93, v62
	v_sub_f32_e32 v93, v93, v60
	v_fma_f32 v3, v93, s50, -v62
	v_cvt_pk_bf16_f32 v2, v2, v3
	ds_write_b16 v9, v2 offset:0
	ds_write_b16_d16_hi v9, v2 offset:144
	v_add_f32_e32 v93, v93, v63
	v_sub_f32_e32 v93, v93, v61
	v_fma_f32 v4, v93, s50, -v63
	v_add_f32_e32 v93, v93, v64
	v_sub_f32_e32 v93, v93, v62
	v_fma_f32 v5, v93, s50, -v64
	v_cvt_pk_bf16_f32 v4, v4, v5
	ds_write_b16 v9, v4 offset:288
	ds_write_b16_d16_hi v9, v4 offset:432
	v_add_f32_e32 v93, v93, v65
	v_sub_f32_e32 v93, v93, v63
	v_fma_f32 v2, v93, s50, -v65
	v_add_f32_e32 v93, v93, v66
	v_sub_f32_e32 v93, v93, v64
	v_fma_f32 v3, v93, s50, -v66
	v_cvt_pk_bf16_f32 v2, v2, v3
	ds_write_b16 v9, v2 offset:576
	ds_write_b16_d16_hi v9, v2 offset:720
	v_add_f32_e32 v93, v93, v67
	v_sub_f32_e32 v93, v93, v65
	v_fma_f32 v4, v93, s50, -v67
	v_add_f32_e32 v93, v93, v68
	v_sub_f32_e32 v93, v93, v66
	v_fma_f32 v5, v93, s50, -v68
	v_cvt_pk_bf16_f32 v4, v4, v5
	ds_write_b16 v9, v4 offset:864
	ds_write_b16_d16_hi v9, v4 offset:1008
	v_add_f32_e32 v93, v93, v69
	v_sub_f32_e32 v93, v93, v67
	v_fma_f32 v2, v93, s50, -v69
	v_add_f32_e32 v93, v93, v70
	v_sub_f32_e32 v93, v93, v68
	v_fma_f32 v3, v93, s50, -v70
	v_cvt_pk_bf16_f32 v2, v2, v3
	ds_write_b16 v9, v2 offset:1152
	ds_write_b16_d16_hi v9, v2 offset:1296
	v_add_f32_e32 v93, v93, v71
	v_sub_f32_e32 v93, v93, v69
	v_fma_f32 v4, v93, s50, -v71
	v_add_f32_e32 v93, v93, v72
	v_sub_f32_e32 v93, v93, v70
	v_fma_f32 v5, v93, s50, -v72
	v_cvt_pk_bf16_f32 v4, v4, v5
	ds_write_b16 v9, v4 offset:1440
	ds_write_b16_d16_hi v9, v4 offset:1584
	v_add_f32_e32 v93, v93, v73
	v_sub_f32_e32 v93, v93, v71
	v_fma_f32 v2, v93, s50, -v73
	v_add_f32_e32 v93, v93, v74
	v_sub_f32_e32 v93, v93, v72
	v_fma_f32 v3, v93, s50, -v74
	v_cvt_pk_bf16_f32 v2, v2, v3
	ds_write_b16 v9, v2 offset:1728
	ds_write_b16_d16_hi v9, v2 offset:1872
	v_add_f32_e32 v93, v93, v75
	v_sub_f32_e32 v93, v93, v73
	v_fma_f32 v4, v93, s50, -v75
	v_add_f32_e32 v93, v93, v76
	v_sub_f32_e32 v93, v93, v74
	v_fma_f32 v5, v93, s50, -v76
	v_cvt_pk_bf16_f32 v4, v4, v5
	ds_write_b16 v9, v4 offset:2016
	ds_write_b16_d16_hi v9, v4 offset:2160
	v_add_f32_e32 v93, v93, v77
	v_sub_f32_e32 v93, v93, v75
	v_fma_f32 v2, v93, s50, -v77
	v_add_f32_e32 v93, v93, v78
	v_sub_f32_e32 v93, v93, v76
	v_fma_f32 v3, v93, s50, -v78
	v_cvt_pk_bf16_f32 v2, v2, v3
	ds_write_b16 v9, v2 offset:2304
	ds_write_b16_d16_hi v9, v2 offset:2448
	v_add_f32_e32 v93, v93, v79
	v_sub_f32_e32 v93, v93, v77
	v_fma_f32 v4, v93, s50, -v79
	v_add_f32_e32 v93, v93, v80
	v_sub_f32_e32 v93, v93, v78
	v_fma_f32 v5, v93, s50, -v80
	v_cvt_pk_bf16_f32 v4, v4, v5
	ds_write_b16 v9, v4 offset:2592
	ds_write_b16_d16_hi v9, v4 offset:2736
	v_add_f32_e32 v93, v93, v81
	v_sub_f32_e32 v93, v93, v79
	v_fma_f32 v2, v93, s50, -v81
	v_add_f32_e32 v93, v93, v82
	v_sub_f32_e32 v93, v93, v80
	v_fma_f32 v3, v93, s50, -v82
	v_cvt_pk_bf16_f32 v2, v2, v3
	ds_write_b16 v9, v2 offset:2880
	ds_write_b16_d16_hi v9, v2 offset:3024
	v_add_f32_e32 v93, v93, v83
	v_sub_f32_e32 v93, v93, v81
	v_fma_f32 v4, v93, s50, -v83
	v_add_f32_e32 v93, v93, v84
	v_sub_f32_e32 v93, v93, v82
	v_fma_f32 v5, v93, s50, -v84
	v_cvt_pk_bf16_f32 v4, v4, v5
	ds_write_b16 v9, v4 offset:3168
	ds_write_b16_d16_hi v9, v4 offset:3312
	v_add_f32_e32 v93, v93, v85
	v_sub_f32_e32 v93, v93, v83
	v_fma_f32 v2, v93, s50, -v85
	v_add_f32_e32 v93, v93, v86
	v_sub_f32_e32 v93, v93, v84
	v_fma_f32 v3, v93, s50, -v86
	v_cvt_pk_bf16_f32 v2, v2, v3
	ds_write_b16 v9, v2 offset:3456
	ds_write_b16_d16_hi v9, v2 offset:3600
	v_add_f32_e32 v93, v93, v87
	v_sub_f32_e32 v93, v93, v85
	v_fma_f32 v4, v93, s50, -v87
	v_add_f32_e32 v93, v93, v88
	v_sub_f32_e32 v93, v93, v86
	v_fma_f32 v5, v93, s50, -v88
	v_cvt_pk_bf16_f32 v4, v4, v5
	ds_write_b16 v9, v4 offset:3744
	ds_write_b16_d16_hi v9, v4 offset:3888
	v_add_f32_e32 v93, v93, v89
	v_sub_f32_e32 v93, v93, v87
	v_fma_f32 v2, v93, s50, -v89
	v_add_f32_e32 v93, v93, v90
	v_sub_f32_e32 v93, v93, v88
	v_fma_f32 v3, v93, s50, -v90
	v_cvt_pk_bf16_f32 v2, v2, v3
	ds_write_b16 v9, v2 offset:4032
	ds_write_b16_d16_hi v9, v2 offset:4176
	v_add_f32_e32 v93, v93, v91
	v_sub_f32_e32 v93, v93, v89
	v_fma_f32 v4, v93, s50, -v91
	v_add_f32_e32 v93, v93, v92
	v_sub_f32_e32 v93, v93, v90
	v_fma_f32 v5, v93, s50, -v92
	v_cvt_pk_bf16_f32 v4, v4, v5
	ds_write_b16 v9, v4 offset:4320
	ds_write_b16_d16_hi v9, v4 offset:4464
	v_and_b32_e32 v2, 31, v0
	v_lshrrev_b32_e32 v3, 5, v0
	v_bfe_u32 v4, v0, 1, 3
	v_xor_b32_e32 v3, v3, v4
	v_lshlrev_b32_e32 v2, 7, v2
	v_add_u32_e32 v2, 0x1a000, v2
	v_lshl_add_u32 v5, v3, 4, v2
	v_xor_b32_e32 v4, 2, v3
	v_lshl_add_u32 v4, v4, 4, v2
	v_xor_b32_e32 v88, 4, v3
	v_xor_b32_e32 v3, 6, v3
	v_lshl_add_u32 v3, v3, 4, v2
	v_lshl_add_u32 v2, v88, 4, v2
	s_waitcnt lgkmcnt(0)
	ds_read_b128 v[28:31], v5 offset:0
	ds_read_b128 v[32:35], v5 offset:4096
	ds_read_b128 v[78:81], v44 offset:0
	ds_read_b128 v[82:85], v44 offset:32
	ds_read_b128 v[86:89], v44 offset:64
	ds_read_b128 v[90:93], v44 offset:96
	ds_read_b128 v[36:39], v4 offset:0
	ds_read_b128 v[40:43], v4 offset:4096
	s_waitcnt lgkmcnt(0)
	v_mfma_f32_32x32x16_bf16 v[46:61], v[28:31], v[78:81], 0
	v_mfma_f32_32x32x16_bf16 v[62:77], v[32:35], v[78:81], 0
	ds_read_b128 v[28:31], v2 offset:0
	ds_read_b128 v[32:35], v2 offset:4096
	v_mfma_f32_32x32x16_bf16 v[46:61], v[36:39], v[82:85], v[46:61]
	v_mfma_f32_32x32x16_bf16 v[62:77], v[40:43], v[82:85], v[62:77]
	ds_read_b128 v[36:39], v3 offset:0
	ds_read_b128 v[40:43], v3 offset:4096
	s_waitcnt lgkmcnt(2)
	v_mfma_f32_32x32x16_bf16 v[46:61], v[28:31], v[86:89], v[46:61]
	v_mfma_f32_32x32x16_bf16 v[62:77], v[32:35], v[86:89], v[62:77]
	s_waitcnt lgkmcnt(0)
	v_mfma_f32_32x32x16_bf16 v[46:61], v[36:39], v[90:93], v[46:61]
	v_mfma_f32_32x32x16_bf16 v[62:77], v[40:43], v[90:93], v[62:77]
	v_lshl_add_u64 v[4:5], s[52:53], 0, v[10:11]
	v_lshl_add_u64 v[98:99], s[52:53], 0, v[96:97]
	s_nop 14
	s_waitcnt vmcnt(5)
	s_mov_b32 s56, 0xbfb8aa3b
	s_mov_b32 s57, 0xbfb8aa3b
	s_mov_b32 s54, 1.0
	s_mov_b32 s55, 1.0
	v_lshlrev_b32_e32 v78, 16, v12
	v_and_b32_e32 v79, 0xffff0000, v12
	v_lshlrev_b32_e32 v80, 16, v13
	v_and_b32_e32 v81, 0xffff0000, v13
	v_lshlrev_b32_e32 v82, 16, v14
	v_and_b32_e32 v83, 0xffff0000, v14
	v_lshlrev_b32_e32 v84, 16, v15
	v_and_b32_e32 v85, 0xffff0000, v15
	v_lshlrev_b32_e32 v86, 16, v16
	v_and_b32_e32 v87, 0xffff0000, v16
	v_lshlrev_b32_e32 v88, 16, v17
	v_and_b32_e32 v89, 0xffff0000, v17
	v_lshlrev_b32_e32 v90, 16, v18
	v_and_b32_e32 v91, 0xffff0000, v18
	v_lshlrev_b32_e32 v92, 16, v19
	v_and_b32_e32 v93, 0xffff0000, v19
	v_pk_mul_f32 v[28:29], v[78:79], s[56:57]
	v_pk_mul_f32 v[30:31], v[80:81], s[56:57]
	v_pk_mul_f32 v[32:33], v[82:83], s[56:57]
	v_pk_mul_f32 v[34:35], v[84:85], s[56:57]
	v_pk_mul_f32 v[36:37], v[86:87], s[56:57]
	v_pk_mul_f32 v[38:39], v[88:89], s[56:57]
	v_pk_mul_f32 v[40:41], v[90:91], s[56:57]
	v_pk_mul_f32 v[42:43], v[92:93], s[56:57]
	v_exp_f32_e32 v28, v28
	v_exp_f32_e32 v29, v29
	v_exp_f32_e32 v30, v30
	v_exp_f32_e32 v31, v31
	v_exp_f32_e32 v32, v32
	v_exp_f32_e32 v33, v33
	v_exp_f32_e32 v34, v34
	v_exp_f32_e32 v35, v35
	v_exp_f32_e32 v36, v36
	v_exp_f32_e32 v37, v37
	v_exp_f32_e32 v38, v38
	v_exp_f32_e32 v39, v39
	v_exp_f32_e32 v40, v40
	v_exp_f32_e32 v41, v41
	v_exp_f32_e32 v42, v42
	v_exp_f32_e32 v43, v43
	v_pk_add_f32 v[28:29], v[28:29], s[54:55]
	v_pk_add_f32 v[30:31], v[30:31], s[54:55]
	v_pk_add_f32 v[32:33], v[32:33], s[54:55]
	v_pk_add_f32 v[34:35], v[34:35], s[54:55]
	v_pk_add_f32 v[36:37], v[36:37], s[54:55]
	v_pk_add_f32 v[38:39], v[38:39], s[54:55]
	v_pk_add_f32 v[40:41], v[40:41], s[54:55]
	v_pk_add_f32 v[42:43], v[42:43], s[54:55]
	v_rcp_f32_e32 v28, v28
	v_rcp_f32_e32 v29, v29
	v_rcp_f32_e32 v30, v30
	v_rcp_f32_e32 v31, v31
	v_rcp_f32_e32 v32, v32
	v_rcp_f32_e32 v33, v33
	v_rcp_f32_e32 v34, v34
	v_rcp_f32_e32 v35, v35
	v_rcp_f32_e32 v36, v36
	v_rcp_f32_e32 v37, v37
	v_rcp_f32_e32 v38, v38
	v_rcp_f32_e32 v39, v39
	v_rcp_f32_e32 v40, v40
	v_rcp_f32_e32 v41, v41
	v_rcp_f32_e32 v42, v42
	v_rcp_f32_e32 v43, v43
	v_pk_mul_f32 v[28:29], v[78:79], v[28:29]
	v_pk_mul_f32 v[30:31], v[80:81], v[30:31]
	v_pk_mul_f32 v[32:33], v[82:83], v[32:33]
	v_pk_mul_f32 v[34:35], v[84:85], v[34:35]
	v_pk_mul_f32 v[36:37], v[86:87], v[36:37]
	v_pk_mul_f32 v[38:39], v[88:89], v[38:39]
	v_pk_mul_f32 v[40:41], v[90:91], v[40:41]
	v_pk_mul_f32 v[42:43], v[92:93], v[42:43]
	v_pk_mul_f32 v[28:29], v[46:47], v[28:29]
	v_pk_mul_f32 v[30:31], v[48:49], v[30:31]
	v_pk_mul_f32 v[32:33], v[50:51], v[32:33]
	v_pk_mul_f32 v[34:35], v[52:53], v[34:35]
	v_pk_mul_f32 v[36:37], v[54:55], v[36:37]
	v_pk_mul_f32 v[38:39], v[56:57], v[38:39]
	v_pk_mul_f32 v[40:41], v[58:59], v[40:41]
	v_pk_mul_f32 v[42:43], v[60:61], v[42:43]
	v_cvt_pk_bf16_f32 v78, v28, v29
	v_cvt_pk_bf16_f32 v79, v30, v31
	v_cvt_pk_bf16_f32 v80, v32, v33
	v_cvt_pk_bf16_f32 v81, v34, v35
	v_cvt_pk_bf16_f32 v82, v36, v37
	v_cvt_pk_bf16_f32 v83, v38, v39
	v_cvt_pk_bf16_f32 v84, v40, v41
	v_cvt_pk_bf16_f32 v85, v42, v43
	s_nop 1
	v_permlane32_swap_b32 v78, v80
	v_permlane32_swap_b32 v79, v81
	v_permlane32_swap_b32 v82, v84
	v_permlane32_swap_b32 v83, v85
	global_store_dwordx4 v[98:99], v[78:81], off offset:0
	global_store_dwordx4 v[98:99], v[82:85], off offset:32
	s_nop 1
	v_lshlrev_b32_e32 v78, 16, v20
	v_and_b32_e32 v79, 0xffff0000, v20
	v_lshlrev_b32_e32 v80, 16, v21
	v_and_b32_e32 v81, 0xffff0000, v21
	v_lshlrev_b32_e32 v82, 16, v22
	v_and_b32_e32 v83, 0xffff0000, v22
	v_lshlrev_b32_e32 v84, 16, v23
	v_and_b32_e32 v85, 0xffff0000, v23
	v_lshlrev_b32_e32 v86, 16, v24
	v_and_b32_e32 v87, 0xffff0000, v24
	v_lshlrev_b32_e32 v88, 16, v25
	v_and_b32_e32 v89, 0xffff0000, v25
	v_lshlrev_b32_e32 v90, 16, v26
	v_and_b32_e32 v91, 0xffff0000, v26
	v_lshlrev_b32_e32 v92, 16, v27
	v_and_b32_e32 v93, 0xffff0000, v27
	v_pk_mul_f32 v[28:29], v[78:79], s[56:57]
	v_pk_mul_f32 v[30:31], v[80:81], s[56:57]
	v_pk_mul_f32 v[32:33], v[82:83], s[56:57]
	v_pk_mul_f32 v[34:35], v[84:85], s[56:57]
	v_pk_mul_f32 v[36:37], v[86:87], s[56:57]
	v_pk_mul_f32 v[38:39], v[88:89], s[56:57]
	v_pk_mul_f32 v[40:41], v[90:91], s[56:57]
	v_pk_mul_f32 v[42:43], v[92:93], s[56:57]
	v_exp_f32_e32 v28, v28
	v_exp_f32_e32 v29, v29
	v_exp_f32_e32 v30, v30
	v_exp_f32_e32 v31, v31
	v_exp_f32_e32 v32, v32
	v_exp_f32_e32 v33, v33
	v_exp_f32_e32 v34, v34
	v_exp_f32_e32 v35, v35
	v_exp_f32_e32 v36, v36
	v_exp_f32_e32 v37, v37
	v_exp_f32_e32 v38, v38
	v_exp_f32_e32 v39, v39
	v_exp_f32_e32 v40, v40
	v_exp_f32_e32 v41, v41
	v_exp_f32_e32 v42, v42
	v_exp_f32_e32 v43, v43
	v_pk_add_f32 v[28:29], v[28:29], s[54:55]
	v_pk_add_f32 v[30:31], v[30:31], s[54:55]
	v_pk_add_f32 v[32:33], v[32:33], s[54:55]
	v_pk_add_f32 v[34:35], v[34:35], s[54:55]
	v_pk_add_f32 v[36:37], v[36:37], s[54:55]
	v_pk_add_f32 v[38:39], v[38:39], s[54:55]
	v_pk_add_f32 v[40:41], v[40:41], s[54:55]
	v_pk_add_f32 v[42:43], v[42:43], s[54:55]
	v_rcp_f32_e32 v28, v28
	v_rcp_f32_e32 v29, v29
	v_rcp_f32_e32 v30, v30
	v_rcp_f32_e32 v31, v31
	v_rcp_f32_e32 v32, v32
	v_rcp_f32_e32 v33, v33
	v_rcp_f32_e32 v34, v34
	v_rcp_f32_e32 v35, v35
	v_rcp_f32_e32 v36, v36
	v_rcp_f32_e32 v37, v37
	v_rcp_f32_e32 v38, v38
	v_rcp_f32_e32 v39, v39
	v_rcp_f32_e32 v40, v40
	v_rcp_f32_e32 v41, v41
	v_rcp_f32_e32 v42, v42
	v_rcp_f32_e32 v43, v43
	v_pk_mul_f32 v[28:29], v[78:79], v[28:29]
	v_pk_mul_f32 v[30:31], v[80:81], v[30:31]
	v_pk_mul_f32 v[32:33], v[82:83], v[32:33]
	v_pk_mul_f32 v[34:35], v[84:85], v[34:35]
	v_pk_mul_f32 v[36:37], v[86:87], v[36:37]
	v_pk_mul_f32 v[38:39], v[88:89], v[38:39]
	v_pk_mul_f32 v[40:41], v[90:91], v[40:41]
	v_pk_mul_f32 v[42:43], v[92:93], v[42:43]
	v_pk_mul_f32 v[28:29], v[62:63], v[28:29]
	v_pk_mul_f32 v[30:31], v[64:65], v[30:31]
	v_pk_mul_f32 v[32:33], v[66:67], v[32:33]
	v_pk_mul_f32 v[34:35], v[68:69], v[34:35]
	v_pk_mul_f32 v[36:37], v[70:71], v[36:37]
	v_pk_mul_f32 v[38:39], v[72:73], v[38:39]
	v_pk_mul_f32 v[40:41], v[74:75], v[40:41]
	v_pk_mul_f32 v[42:43], v[76:77], v[42:43]
	v_cvt_pk_bf16_f32 v78, v28, v29
	v_cvt_pk_bf16_f32 v79, v30, v31
	v_cvt_pk_bf16_f32 v80, v32, v33
	v_cvt_pk_bf16_f32 v81, v34, v35
	v_cvt_pk_bf16_f32 v82, v36, v37
	v_cvt_pk_bf16_f32 v83, v38, v39
	v_cvt_pk_bf16_f32 v84, v40, v41
	v_cvt_pk_bf16_f32 v85, v42, v43
	s_nop 1
	v_permlane32_swap_b32 v78, v80
	v_permlane32_swap_b32 v79, v81
	v_permlane32_swap_b32 v82, v84
	v_permlane32_swap_b32 v83, v85
	global_store_dwordx4 v[98:99], v[78:81], off offset:64
	global_store_dwordx4 v[98:99], v[82:85], off offset:96
	v_lshl_add_u64 v[4:5], s[52:53], 0, v[10:11]
	global_load_dwordx2 v[12:13], v[4:5], off offset:128
	global_load_dwordx2 v[14:15], v[4:5], off offset:144
	global_load_dwordx2 v[16:17], v[4:5], off offset:160
	global_load_dwordx2 v[18:19], v[4:5], off offset:176
	global_load_dwordx2 v[20:21], v[4:5], off offset:192
	global_load_dwordx2 v[22:23], v[4:5], off offset:208
	global_load_dwordx2 v[24:25], v[4:5], off offset:224
	global_load_dwordx2 v[26:27], v[4:5], off offset:240
	s_waitcnt vmcnt(8)
	s_barrier
	s_add_u32 s46, s44, 0x100
	s_addc_u32 s47, s45, 0
	s_add_i32 s43, s48, 0x0
	v_lshl_add_u64 v[4:5], s[46:47], 0, v[6:7]
	s_mov_b32 m0, s43
	s_nop 0
	global_load_lds_dwordx4 v[4:5], off
	s_add_u32 s46, s44, 0x8100
	s_addc_u32 s47, s45, 0
	s_add_i32 s43, s48, 0x2000
	v_lshl_add_u64 v[4:5], s[46:47], 0, v[6:7]
	s_mov_b32 m0, s43
	s_nop 0
	global_load_lds_dwordx4 v[4:5], off
	s_add_u32 s46, s44, 0x10100
	s_addc_u32 s47, s45, 0
	s_add_i32 s43, s48, 0x4000
	v_lshl_add_u64 v[4:5], s[46:47], 0, v[6:7]
	s_mov_b32 m0, s43
	s_nop 0
	global_load_lds_dwordx4 v[4:5], off
	s_add_u32 s46, s44, 0x18100
	s_addc_u32 s47, s45, 0
	s_add_i32 s43, s48, 0x6000
	v_lshl_add_u64 v[4:5], s[46:47], 0, v[6:7]
	s_mov_b32 m0, s43
	s_nop 0
	global_load_lds_dwordx4 v[4:5], off
	s_cmp_lt_u32 s41, 2
	s_cbranch_scc0 .Lpool_xdma_done2
	s_add_u32 s46, s44, 0x20100
	s_addc_u32 s47, s45, 0
	s_add_i32 s43, s48, 0x8000
	v_lshl_add_u64 v[4:5], s[46:47], 0, v[6:7]
	s_mov_b32 m0, s43
	s_nop 0
	global_load_lds_dwordx4 v[4:5], off

.Lpool_nz1:
	v_add_f32_e32 v93, v61, v60
	v_add_f32_e32 v93, v93, v59
	v_add_f32_e32 v93, v93, v58
	s_cmp_eq_u32 s42, 1
	s_cselect_b32 s51, 0x3f800000, s50
	v_fma_f32 v2, v93, s51, -v61
	v_add_f32_e32 v93, v93, v62
	v_sub_f32_e32 v93, v93, v58
	s_cmp_eq_u32 s42, 1
	s_cselect_b32 s51, 0x3f000000, s50
	v_fma_f32 v3, v93, s51, -v62
	v_cvt_pk_bf16_f32 v2, v2, v3
	ds_write_b16 v9, v2 offset:0
	ds_write_b16_d16_hi v9, v2 offset:144
	v_add_f32_e32 v93, v93, v63
	v_sub_f32_e32 v93, v93, v59
	s_cmp_eq_u32 s42, 1
	s_cselect_b32 s51, 0x3eaaaaab, s50
	v_fma_f32 v4, v93, s51, -v63
	v_add_f32_e32 v93, v93, v64
	v_sub_f32_e32 v93, v93, v60
	v_fma_f32 v5, v93, s50, -v64
	v_cvt_pk_bf16_f32 v4, v4, v5
	ds_write_b16 v9, v4 offset:288
	ds_write_b16_d16_hi v9, v4 offset:432
	v_add_f32_e32 v93, v93, v65
	v_sub_f32_e32 v93, v93, v61
	v_fma_f32 v2, v93, s50, -v65
	v_add_f32_e32 v93, v93, v66
	v_sub_f32_e32 v93, v93, v62
	v_fma_f32 v3, v93, s50, -v66
	v_cvt_pk_bf16_f32 v2, v2, v3
	ds_write_b16 v9, v2 offset:576
	ds_write_b16_d16_hi v9, v2 offset:720
	v_add_f32_e32 v93, v93, v67
	v_sub_f32_e32 v93, v93, v63
	v_fma_f32 v4, v93, s50, -v67
	v_add_f32_e32 v93, v93, v68
	v_sub_f32_e32 v93, v93, v64
	v_fma_f32 v5, v93, s50, -v68
	v_cvt_pk_bf16_f32 v4, v4, v5
	ds_write_b16 v9, v4 offset:864
	ds_write_b16_d16_hi v9, v4 offset:1008
	v_add_f32_e32 v93, v93, v69
	v_sub_f32_e32 v93, v93, v65
	v_fma_f32 v2, v93, s50, -v69
	v_add_f32_e32 v93, v93, v70
	v_sub_f32_e32 v93, v93, v66
	v_fma_f32 v3, v93, s50, -v70
	v_cvt_pk_bf16_f32 v2, v2, v3
	ds_write_b16 v9, v2 offset:1152
	ds_write_b16_d16_hi v9, v2 offset:1296
	v_add_f32_e32 v93, v93, v71
	v_sub_f32_e32 v93, v93, v67
	v_fma_f32 v4, v93, s50, -v71
	v_add_f32_e32 v93, v93, v72
	v_sub_f32_e32 v93, v93, v68
	v_fma_f32 v5, v93, s50, -v72
	v_cvt_pk_bf16_f32 v4, v4, v5
	ds_write_b16 v9, v4 offset:1440
	ds_write_b16_d16_hi v9, v4 offset:1584
	v_add_f32_e32 v93, v93, v73
	v_sub_f32_e32 v93, v93, v69
	v_fma_f32 v2, v93, s50, -v73
	v_add_f32_e32 v93, v93, v74
	v_sub_f32_e32 v93, v93, v70
	v_fma_f32 v3, v93, s50, -v74
	v_cvt_pk_bf16_f32 v2, v2, v3
	ds_write_b16 v9, v2 offset:1728
	ds_write_b16_d16_hi v9, v2 offset:1872
	v_add_f32_e32 v93, v93, v75
	v_sub_f32_e32 v93, v93, v71
	v_fma_f32 v4, v93, s50, -v75
	v_add_f32_e32 v93, v93, v76
	v_sub_f32_e32 v93, v93, v72
	v_fma_f32 v5, v93, s50, -v76
	v_cvt_pk_bf16_f32 v4, v4, v5
	ds_write_b16 v9, v4 offset:2016
	ds_write_b16_d16_hi v9, v4 offset:2160
	v_add_f32_e32 v93, v93, v77
	v_sub_f32_e32 v93, v93, v73
	v_fma_f32 v2, v93, s50, -v77
	v_add_f32_e32 v93, v93, v78
	v_sub_f32_e32 v93, v93, v74
	v_fma_f32 v3, v93, s50, -v78
	v_cvt_pk_bf16_f32 v2, v2, v3
	ds_write_b16 v9, v2 offset:2304
	ds_write_b16_d16_hi v9, v2 offset:2448
	v_add_f32_e32 v93, v93, v79
	v_sub_f32_e32 v93, v93, v75
	v_fma_f32 v4, v93, s50, -v79
	v_add_f32_e32 v93, v93, v80
	v_sub_f32_e32 v93, v93, v76
	v_fma_f32 v5, v93, s50, -v80
	v_cvt_pk_bf16_f32 v4, v4, v5
	ds_write_b16 v9, v4 offset:2592
	ds_write_b16_d16_hi v9, v4 offset:2736
	v_add_f32_e32 v93, v93, v81
	v_sub_f32_e32 v93, v93, v77
	v_fma_f32 v2, v93, s50, -v81
	v_add_f32_e32 v93, v93, v82
	v_sub_f32_e32 v93, v93, v78
	v_fma_f32 v3, v93, s50, -v82
	v_cvt_pk_bf16_f32 v2, v2, v3
	ds_write_b16 v9, v2 offset:2880
	ds_write_b16_d16_hi v9, v2 offset:3024
	v_add_f32_e32 v93, v93, v83
	v_sub_f32_e32 v93, v93, v79
	v_fma_f32 v4, v93, s50, -v83
	v_add_f32_e32 v93, v93, v84
	v_sub_f32_e32 v93, v93, v80
	v_fma_f32 v5, v93, s50, -v84
	v_cvt_pk_bf16_f32 v4, v4, v5
	ds_write_b16 v9, v4 offset:3168
	ds_write_b16_d16_hi v9, v4 offset:3312
	v_add_f32_e32 v93, v93, v85
	v_sub_f32_e32 v93, v93, v81
	v_fma_f32 v2, v93, s50, -v85
	v_add_f32_e32 v93, v93, v86
	v_sub_f32_e32 v93, v93, v82
	v_fma_f32 v3, v93, s50, -v86
	v_cvt_pk_bf16_f32 v2, v2, v3
	ds_write_b16 v9, v2 offset:3456
	ds_write_b16_d16_hi v9, v2 offset:3600
	v_add_f32_e32 v93, v93, v87
	v_sub_f32_e32 v93, v93, v83
	v_fma_f32 v4, v93, s50, -v87
	v_add_f32_e32 v93, v93, v88
	v_sub_f32_e32 v93, v93, v84
	v_fma_f32 v5, v93, s50, -v88
	v_cvt_pk_bf16_f32 v4, v4, v5
	ds_write_b16 v9, v4 offset:3744
	ds_write_b16_d16_hi v9, v4 offset:3888
	v_add_f32_e32 v93, v93, v89
	v_sub_f32_e32 v93, v93, v85
	v_fma_f32 v2, v93, s50, -v89
	v_add_f32_e32 v93, v93, v90
	v_sub_f32_e32 v93, v93, v86
	v_fma_f32 v3, v93, s50, -v90
	v_cvt_pk_bf16_f32 v2, v2, v3
	ds_write_b16 v9, v2 offset:4032
	ds_write_b16_d16_hi v9, v2 offset:4176
	v_add_f32_e32 v93, v93, v91
	v_sub_f32_e32 v93, v93, v87
	v_fma_f32 v4, v93, s50, -v91
	v_add_f32_e32 v93, v93, v92
	v_sub_f32_e32 v93, v93, v88
	v_fma_f32 v5, v93, s50, -v92
	v_cvt_pk_bf16_f32 v4, v4, v5
	ds_write_b16 v9, v4 offset:4320
	ds_write_b16_d16_hi v9, v4 offset:4464
	v_and_b32_e32 v2, 31, v0
	v_lshrrev_b32_e32 v3, 5, v0
	v_bfe_u32 v4, v0, 1, 3
	v_xor_b32_e32 v3, v3, v4
	v_lshlrev_b32_e32 v2, 7, v2
	v_add_u32_e32 v2, 0x1c000, v2
	v_lshl_add_u32 v5, v3, 4, v2
	v_xor_b32_e32 v4, 2, v3
	v_lshl_add_u32 v4, v4, 4, v2
	v_xor_b32_e32 v88, 4, v3
	v_xor_b32_e32 v3, 6, v3
	v_lshl_add_u32 v3, v3, 4, v2
	v_lshl_add_u32 v2, v88, 4, v2
	s_waitcnt lgkmcnt(0)
	ds_read_b128 v[28:31], v5 offset:0
	ds_read_b128 v[32:35], v5 offset:4096
	ds_read_b128 v[78:81], v44 offset:0
	ds_read_b128 v[82:85], v44 offset:32
	ds_read_b128 v[86:89], v44 offset:64
	ds_read_b128 v[90:93], v44 offset:96
	ds_read_b128 v[36:39], v4 offset:0
	ds_read_b128 v[40:43], v4 offset:4096
	s_waitcnt lgkmcnt(0)
	v_mfma_f32_32x32x16_bf16 v[46:61], v[28:31], v[78:81], 0
	v_mfma_f32_32x32x16_bf16 v[62:77], v[32:35], v[78:81], 0
	ds_read_b128 v[28:31], v2 offset:0
	ds_read_b128 v[32:35], v2 offset:4096
	v_mfma_f32_32x32x16_bf16 v[46:61], v[36:39], v[82:85], v[46:61]
	v_mfma_f32_32x32x16_bf16 v[62:77], v[40:43], v[82:85], v[62:77]
	ds_read_b128 v[36:39], v3 offset:0
	ds_read_b128 v[40:43], v3 offset:4096
	s_waitcnt lgkmcnt(2)
	v_mfma_f32_32x32x16_bf16 v[46:61], v[28:31], v[86:89], v[46:61]
	v_mfma_f32_32x32x16_bf16 v[62:77], v[32:35], v[86:89], v[62:77]
	s_waitcnt lgkmcnt(0)
	v_mfma_f32_32x32x16_bf16 v[46:61], v[36:39], v[90:93], v[46:61]
	v_mfma_f32_32x32x16_bf16 v[62:77], v[40:43], v[90:93], v[62:77]
	v_lshl_add_u64 v[4:5], s[52:53], 0, v[10:11]
	v_lshl_add_u64 v[98:99], s[52:53], 0, v[96:97]
	s_nop 14
	s_waitcnt vmcnt(5)
	s_mov_b32 s56, 0xbfb8aa3b
	s_mov_b32 s57, 0xbfb8aa3b
	s_mov_b32 s54, 1.0
	s_mov_b32 s55, 1.0
	v_lshlrev_b32_e32 v78, 16, v12
	v_and_b32_e32 v79, 0xffff0000, v12
	v_lshlrev_b32_e32 v80, 16, v13
	v_and_b32_e32 v81, 0xffff0000, v13
	v_lshlrev_b32_e32 v82, 16, v14
	v_and_b32_e32 v83, 0xffff0000, v14
	v_lshlrev_b32_e32 v84, 16, v15
	v_and_b32_e32 v85, 0xffff0000, v15
	v_lshlrev_b32_e32 v86, 16, v16
	v_and_b32_e32 v87, 0xffff0000, v16
	v_lshlrev_b32_e32 v88, 16, v17
	v_and_b32_e32 v89, 0xffff0000, v17
	v_lshlrev_b32_e32 v90, 16, v18
	v_and_b32_e32 v91, 0xffff0000, v18
	v_lshlrev_b32_e32 v92, 16, v19
	v_and_b32_e32 v93, 0xffff0000, v19
	v_pk_mul_f32 v[28:29], v[78:79], s[56:57]
	v_pk_mul_f32 v[30:31], v[80:81], s[56:57]
	v_pk_mul_f32 v[32:33], v[82:83], s[56:57]
	v_pk_mul_f32 v[34:35], v[84:85], s[56:57]
	v_pk_mul_f32 v[36:37], v[86:87], s[56:57]
	v_pk_mul_f32 v[38:39], v[88:89], s[56:57]
	v_pk_mul_f32 v[40:41], v[90:91], s[56:57]
	v_pk_mul_f32 v[42:43], v[92:93], s[56:57]
	v_exp_f32_e32 v28, v28
	v_exp_f32_e32 v29, v29
	v_exp_f32_e32 v30, v30
	v_exp_f32_e32 v31, v31
	v_exp_f32_e32 v32, v32
	v_exp_f32_e32 v33, v33
	v_exp_f32_e32 v34, v34
	v_exp_f32_e32 v35, v35
	v_exp_f32_e32 v36, v36
	v_exp_f32_e32 v37, v37
	v_exp_f32_e32 v38, v38
	v_exp_f32_e32 v39, v39
	v_exp_f32_e32 v40, v40
	v_exp_f32_e32 v41, v41
	v_exp_f32_e32 v42, v42
	v_exp_f32_e32 v43, v43
	v_pk_add_f32 v[28:29], v[28:29], s[54:55]
	v_pk_add_f32 v[30:31], v[30:31], s[54:55]
	v_pk_add_f32 v[32:33], v[32:33], s[54:55]
	v_pk_add_f32 v[34:35], v[34:35], s[54:55]
	v_pk_add_f32 v[36:37], v[36:37], s[54:55]
	v_pk_add_f32 v[38:39], v[38:39], s[54:55]
	v_pk_add_f32 v[40:41], v[40:41], s[54:55]
	v_pk_add_f32 v[42:43], v[42:43], s[54:55]
	v_rcp_f32_e32 v28, v28
	v_rcp_f32_e32 v29, v29
	v_rcp_f32_e32 v30, v30
	v_rcp_f32_e32 v31, v31
	v_rcp_f32_e32 v32, v32
	v_rcp_f32_e32 v33, v33
	v_rcp_f32_e32 v34, v34
	v_rcp_f32_e32 v35, v35
	v_rcp_f32_e32 v36, v36
	v_rcp_f32_e32 v37, v37
	v_rcp_f32_e32 v38, v38
	v_rcp_f32_e32 v39, v39
	v_rcp_f32_e32 v40, v40
	v_rcp_f32_e32 v41, v41
	v_rcp_f32_e32 v42, v42
	v_rcp_f32_e32 v43, v43
	v_pk_mul_f32 v[28:29], v[78:79], v[28:29]
	v_pk_mul_f32 v[30:31], v[80:81], v[30:31]
	v_pk_mul_f32 v[32:33], v[82:83], v[32:33]
	v_pk_mul_f32 v[34:35], v[84:85], v[34:35]
	v_pk_mul_f32 v[36:37], v[86:87], v[36:37]
	v_pk_mul_f32 v[38:39], v[88:89], v[38:39]
	v_pk_mul_f32 v[40:41], v[90:91], v[40:41]
	v_pk_mul_f32 v[42:43], v[92:93], v[42:43]
	v_pk_mul_f32 v[28:29], v[46:47], v[28:29]
	v_pk_mul_f32 v[30:31], v[48:49], v[30:31]
	v_pk_mul_f32 v[32:33], v[50:51], v[32:33]
	v_pk_mul_f32 v[34:35], v[52:53], v[34:35]
	v_pk_mul_f32 v[36:37], v[54:55], v[36:37]
	v_pk_mul_f32 v[38:39], v[56:57], v[38:39]
	v_pk_mul_f32 v[40:41], v[58:59], v[40:41]
	v_pk_mul_f32 v[42:43], v[60:61], v[42:43]
	v_cvt_pk_bf16_f32 v78, v28, v29
	v_cvt_pk_bf16_f32 v79, v30, v31
	v_cvt_pk_bf16_f32 v80, v32, v33
	v_cvt_pk_bf16_f32 v81, v34, v35
	v_cvt_pk_bf16_f32 v82, v36, v37
	v_cvt_pk_bf16_f32 v83, v38, v39
	v_cvt_pk_bf16_f32 v84, v40, v41
	v_cvt_pk_bf16_f32 v85, v42, v43
	s_nop 1
	v_permlane32_swap_b32 v78, v80
	v_permlane32_swap_b32 v79, v81
	v_permlane32_swap_b32 v82, v84
	v_permlane32_swap_b32 v83, v85
	global_store_dwordx4 v[98:99], v[78:81], off offset:128
	global_store_dwordx4 v[98:99], v[82:85], off offset:160
	s_nop 1
	v_lshlrev_b32_e32 v78, 16, v20
	v_and_b32_e32 v79, 0xffff0000, v20
	v_lshlrev_b32_e32 v80, 16, v21
	v_and_b32_e32 v81, 0xffff0000, v21
	v_lshlrev_b32_e32 v82, 16, v22
	v_and_b32_e32 v83, 0xffff0000, v22
	v_lshlrev_b32_e32 v84, 16, v23
	v_and_b32_e32 v85, 0xffff0000, v23
	v_lshlrev_b32_e32 v86, 16, v24
	v_and_b32_e32 v87, 0xffff0000, v24
	v_lshlrev_b32_e32 v88, 16, v25
	v_and_b32_e32 v89, 0xffff0000, v25
	v_lshlrev_b32_e32 v90, 16, v26
	v_and_b32_e32 v91, 0xffff0000, v26
	v_lshlrev_b32_e32 v92, 16, v27
	v_and_b32_e32 v93, 0xffff0000, v27
	v_pk_mul_f32 v[28:29], v[78:79], s[56:57]
	v_pk_mul_f32 v[30:31], v[80:81], s[56:57]
	v_pk_mul_f32 v[32:33], v[82:83], s[56:57]
	v_pk_mul_f32 v[34:35], v[84:85], s[56:57]
	v_pk_mul_f32 v[36:37], v[86:87], s[56:57]
	v_pk_mul_f32 v[38:39], v[88:89], s[56:57]
	v_pk_mul_f32 v[40:41], v[90:91], s[56:57]
	v_pk_mul_f32 v[42:43], v[92:93], s[56:57]
	v_exp_f32_e32 v28, v28
	v_exp_f32_e32 v29, v29
	v_exp_f32_e32 v30, v30
	v_exp_f32_e32 v31, v31
	v_exp_f32_e32 v32, v32
	v_exp_f32_e32 v33, v33
	v_exp_f32_e32 v34, v34
	v_exp_f32_e32 v35, v35
	v_exp_f32_e32 v36, v36
	v_exp_f32_e32 v37, v37
	v_exp_f32_e32 v38, v38
	v_exp_f32_e32 v39, v39
	v_exp_f32_e32 v40, v40
	v_exp_f32_e32 v41, v41
	v_exp_f32_e32 v42, v42
	v_exp_f32_e32 v43, v43
	v_pk_add_f32 v[28:29], v[28:29], s[54:55]
	v_pk_add_f32 v[30:31], v[30:31], s[54:55]
	v_pk_add_f32 v[32:33], v[32:33], s[54:55]
	v_pk_add_f32 v[34:35], v[34:35], s[54:55]
	v_pk_add_f32 v[36:37], v[36:37], s[54:55]
	v_pk_add_f32 v[38:39], v[38:39], s[54:55]
	v_pk_add_f32 v[40:41], v[40:41], s[54:55]
	v_pk_add_f32 v[42:43], v[42:43], s[54:55]
	v_rcp_f32_e32 v28, v28
	v_rcp_f32_e32 v29, v29
	v_rcp_f32_e32 v30, v30
	v_rcp_f32_e32 v31, v31
	v_rcp_f32_e32 v32, v32
	v_rcp_f32_e32 v33, v33
	v_rcp_f32_e32 v34, v34
	v_rcp_f32_e32 v35, v35
	v_rcp_f32_e32 v36, v36
	v_rcp_f32_e32 v37, v37
	v_rcp_f32_e32 v38, v38
	v_rcp_f32_e32 v39, v39
	v_rcp_f32_e32 v40, v40
	v_rcp_f32_e32 v41, v41
	v_rcp_f32_e32 v42, v42
	v_rcp_f32_e32 v43, v43
	v_pk_mul_f32 v[28:29], v[78:79], v[28:29]
	v_pk_mul_f32 v[30:31], v[80:81], v[30:31]
	v_pk_mul_f32 v[32:33], v[82:83], v[32:33]
	v_pk_mul_f32 v[34:35], v[84:85], v[34:35]
	v_pk_mul_f32 v[36:37], v[86:87], v[36:37]
	v_pk_mul_f32 v[38:39], v[88:89], v[38:39]
	v_pk_mul_f32 v[40:41], v[90:91], v[40:41]
	v_pk_mul_f32 v[42:43], v[92:93], v[42:43]
	v_pk_mul_f32 v[28:29], v[62:63], v[28:29]
	v_pk_mul_f32 v[30:31], v[64:65], v[30:31]
	v_pk_mul_f32 v[32:33], v[66:67], v[32:33]
	v_pk_mul_f32 v[34:35], v[68:69], v[34:35]
	v_pk_mul_f32 v[36:37], v[70:71], v[36:37]
	v_pk_mul_f32 v[38:39], v[72:73], v[38:39]
	v_pk_mul_f32 v[40:41], v[74:75], v[40:41]
	v_pk_mul_f32 v[42:43], v[76:77], v[42:43]
	v_cvt_pk_bf16_f32 v78, v28, v29
	v_cvt_pk_bf16_f32 v79, v30, v31
	v_cvt_pk_bf16_f32 v80, v32, v33
	v_cvt_pk_bf16_f32 v81, v34, v35
	v_cvt_pk_bf16_f32 v82, v36, v37
	v_cvt_pk_bf16_f32 v83, v38, v39
	v_cvt_pk_bf16_f32 v84, v40, v41
	v_cvt_pk_bf16_f32 v85, v42, v43
	s_nop 1
	v_permlane32_swap_b32 v78, v80
	v_permlane32_swap_b32 v79, v81
	v_permlane32_swap_b32 v82, v84
	v_permlane32_swap_b32 v83, v85
	global_store_dwordx4 v[98:99], v[78:81], off offset:192
	global_store_dwordx4 v[98:99], v[82:85], off offset:224
	v_lshl_add_u64 v[4:5], s[52:53], 0, v[10:11]
	global_load_dwordx2 v[12:13], v[4:5], off offset:256
	global_load_dwordx2 v[14:15], v[4:5], off offset:272
	global_load_dwordx2 v[16:17], v[4:5], off offset:288
	global_load_dwordx2 v[18:19], v[4:5], off offset:304
	global_load_dwordx2 v[20:21], v[4:5], off offset:320
	global_load_dwordx2 v[22:23], v[4:5], off offset:336
	global_load_dwordx2 v[24:25], v[4:5], off offset:352
	global_load_dwordx2 v[26:27], v[4:5], off offset:368
	s_waitcnt vmcnt(8)
	s_barrier
	s_add_u32 s46, s44, 0x180
	s_addc_u32 s47, s45, 0
	s_add_i32 s43, s48, 0x8800
	v_lshl_add_u64 v[4:5], s[46:47], 0, v[6:7]
	s_mov_b32 m0, s43
	s_nop 0
	global_load_lds_dwordx4 v[4:5], off
	s_add_u32 s46, s44, 0x8180
	s_addc_u32 s47, s45, 0
	s_add_i32 s43, s48, 0xa800
	v_lshl_add_u64 v[4:5], s[46:47], 0, v[6:7]
	s_mov_b32 m0, s43
	s_nop 0
	global_load_lds_dwordx4 v[4:5], off
	s_add_u32 s46, s44, 0x10180
	s_addc_u32 s47, s45, 0
	s_add_i32 s43, s48, 0xc800
	v_lshl_add_u64 v[4:5], s[46:47], 0, v[6:7]
	s_mov_b32 m0, s43
	s_nop 0
	global_load_lds_dwordx4 v[4:5], off
	s_add_u32 s46, s44, 0x18180
	s_addc_u32 s47, s45, 0
	s_add_i32 s43, s48, 0xe800
	v_lshl_add_u64 v[4:5], s[46:47], 0, v[6:7]
	s_mov_b32 m0, s43
	s_nop 0
	global_load_lds_dwordx4 v[4:5], off
	s_cmp_lt_u32 s41, 2
	s_cbranch_scc0 .Lpool_xdma_done3
	s_add_u32 s46, s44, 0x20180
	s_addc_u32 s47, s45, 0
	s_add_i32 s43, s48, 0x10800
	v_lshl_add_u64 v[4:5], s[46:47], 0, v[6:7]
	s_mov_b32 m0, s43
	s_nop 0
	global_load_lds_dwordx4 v[4:5], off

.Lpool_nz2:
	v_add_f32_e32 v93, v61, v60
	v_add_f32_e32 v93, v93, v59
	v_add_f32_e32 v93, v93, v58
	v_add_f32_e32 v93, v93, v57
	v_add_f32_e32 v93, v93, v56
	v_add_f32_e32 v93, v93, v55
	v_add_f32_e32 v93, v93, v54
	s_cmp_eq_u32 s42, 1
	s_cselect_b32 s51, 0x3f800000, s50
	v_fma_f32 v2, v93, s51, -v61
	v_add_f32_e32 v93, v93, v62
	v_sub_f32_e32 v93, v93, v54
	s_cmp_eq_u32 s42, 1
	s_cselect_b32 s51, 0x3f000000, s50
	v_fma_f32 v3, v93, s51, -v62
	v_cvt_pk_bf16_f32 v2, v2, v3
	ds_write_b16 v9, v2 offset:0
	ds_write_b16_d16_hi v9, v2 offset:144
	v_add_f32_e32 v93, v93, v63
	v_sub_f32_e32 v93, v93, v55
	s_cmp_eq_u32 s42, 1
	s_cselect_b32 s51, 0x3eaaaaab, s50
	v_fma_f32 v4, v93, s51, -v63
	v_add_f32_e32 v93, v93, v64
	v_sub_f32_e32 v93, v93, v56
	s_cmp_eq_u32 s42, 1
	s_cselect_b32 s51, 0x3e800000, s50
	v_fma_f32 v5, v93, s51, -v64
	v_cvt_pk_bf16_f32 v4, v4, v5
	ds_write_b16 v9, v4 offset:288
	ds_write_b16_d16_hi v9, v4 offset:432
	v_add_f32_e32 v93, v93, v65
	v_sub_f32_e32 v93, v93, v57
	s_cmp_eq_u32 s42, 1
	s_cselect_b32 s51, 0x3e4ccccd, s50
	v_fma_f32 v2, v93, s51, -v65
	v_add_f32_e32 v93, v93, v66
	v_sub_f32_e32 v93, v93, v58
	s_cmp_eq_u32 s42, 1
	s_cselect_b32 s51, 0x3e2aaaab, s50
	v_fma_f32 v3, v93, s51, -v66
	v_cvt_pk_bf16_f32 v2, v2, v3
	ds_write_b16 v9, v2 offset:576
	ds_write_b16_d16_hi v9, v2 offset:720
	v_add_f32_e32 v93, v93, v67
	v_sub_f32_e32 v93, v93, v59
	s_cmp_eq_u32 s42, 1
	s_cselect_b32 s51, 0x3e124925, s50
	v_fma_f32 v4, v93, s51, -v67
	v_add_f32_e32 v93, v93, v68
	v_sub_f32_e32 v93, v93, v60
	v_fma_f32 v5, v93, s50, -v68
	v_cvt_pk_bf16_f32 v4, v4, v5
	ds_write_b16 v9, v4 offset:864
	ds_write_b16_d16_hi v9, v4 offset:1008
	v_add_f32_e32 v93, v93, v69
	v_sub_f32_e32 v93, v93, v61
	v_fma_f32 v2, v93, s50, -v69
	v_add_f32_e32 v93, v93, v70
	v_sub_f32_e32 v93, v93, v62
	v_fma_f32 v3, v93, s50, -v70
	v_cvt_pk_bf16_f32 v2, v2, v3
	ds_write_b16 v9, v2 offset:1152
	ds_write_b16_d16_hi v9, v2 offset:1296
	v_add_f32_e32 v93, v93, v71
	v_sub_f32_e32 v93, v93, v63
	v_fma_f32 v4, v93, s50, -v71
	v_add_f32_e32 v93, v93, v72
	v_sub_f32_e32 v93, v93, v64
	v_fma_f32 v5, v93, s50, -v72
	v_cvt_pk_bf16_f32 v4, v4, v5
	ds_write_b16 v9, v4 offset:1440
	ds_write_b16_d16_hi v9, v4 offset:1584
	v_add_f32_e32 v93, v93, v73
	v_sub_f32_e32 v93, v93, v65
	v_fma_f32 v2, v93, s50, -v73
	v_add_f32_e32 v93, v93, v74
	v_sub_f32_e32 v93, v93, v66
	v_fma_f32 v3, v93, s50, -v74
	v_cvt_pk_bf16_f32 v2, v2, v3
	ds_write_b16 v9, v2 offset:1728
	ds_write_b16_d16_hi v9, v2 offset:1872
	v_add_f32_e32 v93, v93, v75
	v_sub_f32_e32 v93, v93, v67
	v_fma_f32 v4, v93, s50, -v75
	v_add_f32_e32 v93, v93, v76
	v_sub_f32_e32 v93, v93, v68
	v_fma_f32 v5, v93, s50, -v76
	v_cvt_pk_bf16_f32 v4, v4, v5
	ds_write_b16 v9, v4 offset:2016
	ds_write_b16_d16_hi v9, v4 offset:2160
	v_add_f32_e32 v93, v93, v77
	v_sub_f32_e32 v93, v93, v69
	v_fma_f32 v2, v93, s50, -v77
	v_add_f32_e32 v93, v93, v78
	v_sub_f32_e32 v93, v93, v70
	v_fma_f32 v3, v93, s50, -v78
	v_cvt_pk_bf16_f32 v2, v2, v3
	ds_write_b16 v9, v2 offset:2304
	ds_write_b16_d16_hi v9, v2 offset:2448
	v_add_f32_e32 v93, v93, v79
	v_sub_f32_e32 v93, v93, v71
	v_fma_f32 v4, v93, s50, -v79
	v_add_f32_e32 v93, v93, v80
	v_sub_f32_e32 v93, v93, v72
	v_fma_f32 v5, v93, s50, -v80
	v_cvt_pk_bf16_f32 v4, v4, v5
	ds_write_b16 v9, v4 offset:2592
	ds_write_b16_d16_hi v9, v4 offset:2736
	v_add_f32_e32 v93, v93, v81
	v_sub_f32_e32 v93, v93, v73
	v_fma_f32 v2, v93, s50, -v81
	v_add_f32_e32 v93, v93, v82
	v_sub_f32_e32 v93, v93, v74
	v_fma_f32 v3, v93, s50, -v82
	v_cvt_pk_bf16_f32 v2, v2, v3
	ds_write_b16 v9, v2 offset:2880
	ds_write_b16_d16_hi v9, v2 offset:3024
	v_add_f32_e32 v93, v93, v83
	v_sub_f32_e32 v93, v93, v75
	v_fma_f32 v4, v93, s50, -v83
	v_add_f32_e32 v93, v93, v84
	v_sub_f32_e32 v93, v93, v76
	v_fma_f32 v5, v93, s50, -v84
	v_cvt_pk_bf16_f32 v4, v4, v5
	ds_write_b16 v9, v4 offset:3168
	ds_write_b16_d16_hi v9, v4 offset:3312
	v_add_f32_e32 v93, v93, v85
	v_sub_f32_e32 v93, v93, v77
	v_fma_f32 v2, v93, s50, -v85
	v_add_f32_e32 v93, v93, v86
	v_sub_f32_e32 v93, v93, v78
	v_fma_f32 v3, v93, s50, -v86
	v_cvt_pk_bf16_f32 v2, v2, v3
	ds_write_b16 v9, v2 offset:3456
	ds_write_b16_d16_hi v9, v2 offset:3600
	v_add_f32_e32 v93, v93, v87
	v_sub_f32_e32 v93, v93, v79
	v_fma_f32 v4, v93, s50, -v87
	v_add_f32_e32 v93, v93, v88
	v_sub_f32_e32 v93, v93, v80
	v_fma_f32 v5, v93, s50, -v88
	v_cvt_pk_bf16_f32 v4, v4, v5
	ds_write_b16 v9, v4 offset:3744
	ds_write_b16_d16_hi v9, v4 offset:3888
	v_add_f32_e32 v93, v93, v89
	v_sub_f32_e32 v93, v93, v81
	v_fma_f32 v2, v93, s50, -v89
	v_add_f32_e32 v93, v93, v90
	v_sub_f32_e32 v93, v93, v82
	v_fma_f32 v3, v93, s50, -v90
	v_cvt_pk_bf16_f32 v2, v2, v3
	ds_write_b16 v9, v2 offset:4032
	ds_write_b16_d16_hi v9, v2 offset:4176
	v_add_f32_e32 v93, v93, v91
	v_sub_f32_e32 v93, v93, v83
	v_fma_f32 v4, v93, s50, -v91
	v_add_f32_e32 v93, v93, v92
	v_sub_f32_e32 v93, v93, v84
	v_fma_f32 v5, v93, s50, -v92
	v_cvt_pk_bf16_f32 v4, v4, v5
	ds_write_b16 v9, v4 offset:4320
	ds_write_b16_d16_hi v9, v4 offset:4464
	v_and_b32_e32 v2, 31, v0
	v_lshrrev_b32_e32 v3, 5, v0
	v_bfe_u32 v4, v0, 1, 3
	v_xor_b32_e32 v3, v3, v4
	v_lshlrev_b32_e32 v2, 7, v2
	v_add_u32_e32 v2, 0x1a000, v2
	v_lshl_add_u32 v5, v3, 4, v2
	v_xor_b32_e32 v4, 2, v3
	v_lshl_add_u32 v4, v4, 4, v2
	v_xor_b32_e32 v88, 4, v3
	v_xor_b32_e32 v3, 6, v3
	v_lshl_add_u32 v3, v3, 4, v2
	v_lshl_add_u32 v2, v88, 4, v2
	s_waitcnt lgkmcnt(0)
	ds_read_b128 v[28:31], v5 offset:0
	ds_read_b128 v[32:35], v5 offset:4096
	ds_read_b128 v[78:81], v44 offset:0
	ds_read_b128 v[82:85], v44 offset:32
	ds_read_b128 v[86:89], v44 offset:64
	ds_read_b128 v[90:93], v44 offset:96
	ds_read_b128 v[36:39], v4 offset:0
	ds_read_b128 v[40:43], v4 offset:4096
	s_waitcnt lgkmcnt(0)
	v_mfma_f32_32x32x16_bf16 v[46:61], v[28:31], v[78:81], 0
	v_mfma_f32_32x32x16_bf16 v[62:77], v[32:35], v[78:81], 0
	ds_read_b128 v[28:31], v2 offset:0
	ds_read_b128 v[32:35], v2 offset:4096
	v_mfma_f32_32x32x16_bf16 v[46:61], v[36:39], v[82:85], v[46:61]
	v_mfma_f32_32x32x16_bf16 v[62:77], v[40:43], v[82:85], v[62:77]
	ds_read_b128 v[36:39], v3 offset:0
	ds_read_b128 v[40:43], v3 offset:4096
	s_waitcnt lgkmcnt(2)
	v_mfma_f32_32x32x16_bf16 v[46:61], v[28:31], v[86:89], v[46:61]
	v_mfma_f32_32x32x16_bf16 v[62:77], v[32:35], v[86:89], v[62:77]
	s_waitcnt lgkmcnt(0)
	v_mfma_f32_32x32x16_bf16 v[46:61], v[36:39], v[90:93], v[46:61]
	v_mfma_f32_32x32x16_bf16 v[62:77], v[40:43], v[90:93], v[62:77]
	v_lshl_add_u64 v[4:5], s[52:53], 0, v[10:11]
	v_lshl_add_u64 v[98:99], s[52:53], 0, v[96:97]
	s_nop 14
	s_waitcnt vmcnt(5)
	s_mov_b32 s56, 0xbfb8aa3b
	s_mov_b32 s57, 0xbfb8aa3b
	s_mov_b32 s54, 1.0
	s_mov_b32 s55, 1.0
	v_lshlrev_b32_e32 v78, 16, v12
	v_and_b32_e32 v79, 0xffff0000, v12
	v_lshlrev_b32_e32 v80, 16, v13
	v_and_b32_e32 v81, 0xffff0000, v13
	v_lshlrev_b32_e32 v82, 16, v14
	v_and_b32_e32 v83, 0xffff0000, v14
	v_lshlrev_b32_e32 v84, 16, v15
	v_and_b32_e32 v85, 0xffff0000, v15
	v_lshlrev_b32_e32 v86, 16, v16
	v_and_b32_e32 v87, 0xffff0000, v16
	v_lshlrev_b32_e32 v88, 16, v17
	v_and_b32_e32 v89, 0xffff0000, v17
	v_lshlrev_b32_e32 v90, 16, v18
	v_and_b32_e32 v91, 0xffff0000, v18
	v_lshlrev_b32_e32 v92, 16, v19
	v_and_b32_e32 v93, 0xffff0000, v19
	v_pk_mul_f32 v[28:29], v[78:79], s[56:57]
	v_pk_mul_f32 v[30:31], v[80:81], s[56:57]
	v_pk_mul_f32 v[32:33], v[82:83], s[56:57]
	v_pk_mul_f32 v[34:35], v[84:85], s[56:57]
	v_pk_mul_f32 v[36:37], v[86:87], s[56:57]
	v_pk_mul_f32 v[38:39], v[88:89], s[56:57]
	v_pk_mul_f32 v[40:41], v[90:91], s[56:57]
	v_pk_mul_f32 v[42:43], v[92:93], s[56:57]
	v_exp_f32_e32 v28, v28
	v_exp_f32_e32 v29, v29
	v_exp_f32_e32 v30, v30
	v_exp_f32_e32 v31, v31
	v_exp_f32_e32 v32, v32
	v_exp_f32_e32 v33, v33
	v_exp_f32_e32 v34, v34
	v_exp_f32_e32 v35, v35
	v_exp_f32_e32 v36, v36
	v_exp_f32_e32 v37, v37
	v_exp_f32_e32 v38, v38
	v_exp_f32_e32 v39, v39
	v_exp_f32_e32 v40, v40
	v_exp_f32_e32 v41, v41
	v_exp_f32_e32 v42, v42
	v_exp_f32_e32 v43, v43
	v_pk_add_f32 v[28:29], v[28:29], s[54:55]
	v_pk_add_f32 v[30:31], v[30:31], s[54:55]
	v_pk_add_f32 v[32:33], v[32:33], s[54:55]
	v_pk_add_f32 v[34:35], v[34:35], s[54:55]
	v_pk_add_f32 v[36:37], v[36:37], s[54:55]
	v_pk_add_f32 v[38:39], v[38:39], s[54:55]
	v_pk_add_f32 v[40:41], v[40:41], s[54:55]
	v_pk_add_f32 v[42:43], v[42:43], s[54:55]
	v_rcp_f32_e32 v28, v28
	v_rcp_f32_e32 v29, v29
	v_rcp_f32_e32 v30, v30
	v_rcp_f32_e32 v31, v31
	v_rcp_f32_e32 v32, v32
	v_rcp_f32_e32 v33, v33
	v_rcp_f32_e32 v34, v34
	v_rcp_f32_e32 v35, v35
	v_rcp_f32_e32 v36, v36
	v_rcp_f32_e32 v37, v37
	v_rcp_f32_e32 v38, v38
	v_rcp_f32_e32 v39, v39
	v_rcp_f32_e32 v40, v40
	v_rcp_f32_e32 v41, v41
	v_rcp_f32_e32 v42, v42
	v_rcp_f32_e32 v43, v43
	v_pk_mul_f32 v[28:29], v[78:79], v[28:29]
	v_pk_mul_f32 v[30:31], v[80:81], v[30:31]
	v_pk_mul_f32 v[32:33], v[82:83], v[32:33]
	v_pk_mul_f32 v[34:35], v[84:85], v[34:35]
	v_pk_mul_f32 v[36:37], v[86:87], v[36:37]
	v_pk_mul_f32 v[38:39], v[88:89], v[38:39]
	v_pk_mul_f32 v[40:41], v[90:91], v[40:41]
	v_pk_mul_f32 v[42:43], v[92:93], v[42:43]
	v_pk_mul_f32 v[28:29], v[46:47], v[28:29]
	v_pk_mul_f32 v[30:31], v[48:49], v[30:31]
	v_pk_mul_f32 v[32:33], v[50:51], v[32:33]
	v_pk_mul_f32 v[34:35], v[52:53], v[34:35]
	v_pk_mul_f32 v[36:37], v[54:55], v[36:37]
	v_pk_mul_f32 v[38:39], v[56:57], v[38:39]
	v_pk_mul_f32 v[40:41], v[58:59], v[40:41]
	v_pk_mul_f32 v[42:43], v[60:61], v[42:43]
	v_cvt_pk_bf16_f32 v78, v28, v29
	v_cvt_pk_bf16_f32 v79, v30, v31
	v_cvt_pk_bf16_f32 v80, v32, v33
	v_cvt_pk_bf16_f32 v81, v34, v35
	v_cvt_pk_bf16_f32 v82, v36, v37
	v_cvt_pk_bf16_f32 v83, v38, v39
	v_cvt_pk_bf16_f32 v84, v40, v41
	v_cvt_pk_bf16_f32 v85, v42, v43
	s_nop 1
	v_permlane32_swap_b32 v78, v80
	v_permlane32_swap_b32 v79, v81
	v_permlane32_swap_b32 v82, v84
	v_permlane32_swap_b32 v83, v85
	global_store_dwordx4 v[98:99], v[78:81], off offset:256
	global_store_dwordx4 v[98:99], v[82:85], off offset:288
	s_nop 1
	v_lshlrev_b32_e32 v78, 16, v20
	v_and_b32_e32 v79, 0xffff0000, v20
	v_lshlrev_b32_e32 v80, 16, v21
	v_and_b32_e32 v81, 0xffff0000, v21
	v_lshlrev_b32_e32 v82, 16, v22
	v_and_b32_e32 v83, 0xffff0000, v22
	v_lshlrev_b32_e32 v84, 16, v23
	v_and_b32_e32 v85, 0xffff0000, v23
	v_lshlrev_b32_e32 v86, 16, v24
	v_and_b32_e32 v87, 0xffff0000, v24
	v_lshlrev_b32_e32 v88, 16, v25
	v_and_b32_e32 v89, 0xffff0000, v25
	v_lshlrev_b32_e32 v90, 16, v26
	v_and_b32_e32 v91, 0xffff0000, v26
	v_lshlrev_b32_e32 v92, 16, v27
	v_and_b32_e32 v93, 0xffff0000, v27
	v_pk_mul_f32 v[28:29], v[78:79], s[56:57]
	v_pk_mul_f32 v[30:31], v[80:81], s[56:57]
	v_pk_mul_f32 v[32:33], v[82:83], s[56:57]
	v_pk_mul_f32 v[34:35], v[84:85], s[56:57]
	v_pk_mul_f32 v[36:37], v[86:87], s[56:57]
	v_pk_mul_f32 v[38:39], v[88:89], s[56:57]
	v_pk_mul_f32 v[40:41], v[90:91], s[56:57]
	v_pk_mul_f32 v[42:43], v[92:93], s[56:57]
	v_exp_f32_e32 v28, v28
	v_exp_f32_e32 v29, v29
	v_exp_f32_e32 v30, v30
	v_exp_f32_e32 v31, v31
	v_exp_f32_e32 v32, v32
	v_exp_f32_e32 v33, v33
	v_exp_f32_e32 v34, v34
	v_exp_f32_e32 v35, v35
	v_exp_f32_e32 v36, v36
	v_exp_f32_e32 v37, v37
	v_exp_f32_e32 v38, v38
	v_exp_f32_e32 v39, v39
	v_exp_f32_e32 v40, v40
	v_exp_f32_e32 v41, v41
	v_exp_f32_e32 v42, v42
	v_exp_f32_e32 v43, v43
	v_pk_add_f32 v[28:29], v[28:29], s[54:55]
	v_pk_add_f32 v[30:31], v[30:31], s[54:55]
	v_pk_add_f32 v[32:33], v[32:33], s[54:55]
	v_pk_add_f32 v[34:35], v[34:35], s[54:55]
	v_pk_add_f32 v[36:37], v[36:37], s[54:55]
	v_pk_add_f32 v[38:39], v[38:39], s[54:55]
	v_pk_add_f32 v[40:41], v[40:41], s[54:55]
	v_pk_add_f32 v[42:43], v[42:43], s[54:55]
	v_rcp_f32_e32 v28, v28
	v_rcp_f32_e32 v29, v29
	v_rcp_f32_e32 v30, v30
	v_rcp_f32_e32 v31, v31
	v_rcp_f32_e32 v32, v32
	v_rcp_f32_e32 v33, v33
	v_rcp_f32_e32 v34, v34
	v_rcp_f32_e32 v35, v35
	v_rcp_f32_e32 v36, v36
	v_rcp_f32_e32 v37, v37
	v_rcp_f32_e32 v38, v38
	v_rcp_f32_e32 v39, v39
	v_rcp_f32_e32 v40, v40
	v_rcp_f32_e32 v41, v41
	v_rcp_f32_e32 v42, v42
	v_rcp_f32_e32 v43, v43
	v_pk_mul_f32 v[28:29], v[78:79], v[28:29]
	v_pk_mul_f32 v[30:31], v[80:81], v[30:31]
	v_pk_mul_f32 v[32:33], v[82:83], v[32:33]
	v_pk_mul_f32 v[34:35], v[84:85], v[34:35]
	v_pk_mul_f32 v[36:37], v[86:87], v[36:37]
	v_pk_mul_f32 v[38:39], v[88:89], v[38:39]
	v_pk_mul_f32 v[40:41], v[90:91], v[40:41]
	v_pk_mul_f32 v[42:43], v[92:93], v[42:43]
	v_pk_mul_f32 v[28:29], v[62:63], v[28:29]
	v_pk_mul_f32 v[30:31], v[64:65], v[30:31]
	v_pk_mul_f32 v[32:33], v[66:67], v[32:33]
	v_pk_mul_f32 v[34:35], v[68:69], v[34:35]
	v_pk_mul_f32 v[36:37], v[70:71], v[36:37]
	v_pk_mul_f32 v[38:39], v[72:73], v[38:39]
	v_pk_mul_f32 v[40:41], v[74:75], v[40:41]
	v_pk_mul_f32 v[42:43], v[76:77], v[42:43]
	v_cvt_pk_bf16_f32 v78, v28, v29
	v_cvt_pk_bf16_f32 v79, v30, v31
	v_cvt_pk_bf16_f32 v80, v32, v33
	v_cvt_pk_bf16_f32 v81, v34, v35
	v_cvt_pk_bf16_f32 v82, v36, v37
	v_cvt_pk_bf16_f32 v83, v38, v39
	v_cvt_pk_bf16_f32 v84, v40, v41
	v_cvt_pk_bf16_f32 v85, v42, v43
	s_nop 1
	v_permlane32_swap_b32 v78, v80
	v_permlane32_swap_b32 v79, v81
	v_permlane32_swap_b32 v82, v84
	v_permlane32_swap_b32 v83, v85
	global_store_dwordx4 v[98:99], v[78:81], off offset:320
	global_store_dwordx4 v[98:99], v[82:85], off offset:352
	v_lshl_add_u64 v[4:5], s[52:53], 0, v[10:11]
	global_load_dwordx2 v[12:13], v[4:5], off offset:384
	global_load_dwordx2 v[14:15], v[4:5], off offset:400
	global_load_dwordx2 v[16:17], v[4:5], off offset:416
	global_load_dwordx2 v[18:19], v[4:5], off offset:432
	global_load_dwordx2 v[20:21], v[4:5], off offset:448
	global_load_dwordx2 v[22:23], v[4:5], off offset:464
	global_load_dwordx2 v[24:25], v[4:5], off offset:480
	global_load_dwordx2 v[26:27], v[4:5], off offset:496
	s_waitcnt vmcnt(8)
	s_barrier
	ds_read_u16 v46, v8 offset:34816
	ds_read_u16 v47, v8 offset:34944
	ds_read_u16 v48, v8 offset:35072
	ds_read_u16 v49, v8 offset:35200
	ds_read_u16 v50, v8 offset:35328
	ds_read_u16 v51, v8 offset:35456
	ds_read_u16 v52, v8 offset:35584
	ds_read_u16 v53, v8 offset:35712
	ds_read_u16 v54, v8 offset:35840
	ds_read_u16 v55, v8 offset:35968
	ds_read_u16 v56, v8 offset:36096
	ds_read_u16 v57, v8 offset:36224
	ds_read_u16 v58, v8 offset:36352
	ds_read_u16 v59, v8 offset:36480
	ds_read_u16 v60, v8 offset:36608
	ds_read_u16 v61, v8 offset:36736
	ds_read_u16 v62, v8 offset:36864
	ds_read_u16 v63, v8 offset:36992
	ds_read_u16 v64, v8 offset:37120
	ds_read_u16 v65, v8 offset:37248
	ds_read_u16 v66, v8 offset:37376
	ds_read_u16 v67, v8 offset:37504
	ds_read_u16 v68, v8 offset:37632
	ds_read_u16 v69, v8 offset:37760
	ds_read_u16 v70, v8 offset:37888
	ds_read_u16 v71, v8 offset:38016
	ds_read_u16 v72, v8 offset:38144
	ds_read_u16 v73, v8 offset:38272
	ds_read_u16 v74, v8 offset:38400
	ds_read_u16 v75, v8 offset:38528
	ds_read_u16 v76, v8 offset:38656
	ds_read_u16 v77, v8 offset:38784
	ds_read_u16 v78, v8 offset:38912
	ds_read_u16 v79, v8 offset:39040
	ds_read_u16 v80, v8 offset:39168
	ds_read_u16 v81, v8 offset:39296
	ds_read_u16 v82, v8 offset:39424
	ds_read_u16 v83, v8 offset:39552
	ds_read_u16 v84, v8 offset:39680
	ds_read_u16 v85, v8 offset:39808
	ds_read_u16 v86, v8 offset:39936
	ds_read_u16 v87, v8 offset:40064
	ds_read_u16 v88, v8 offset:40192
	ds_read_u16 v89, v8 offset:40320
	ds_read_u16 v90, v8 offset:40448
	ds_read_u16 v91, v8 offset:40576
	ds_read_u16 v92, v8 offset:40704
	s_mov_b32 s50, 0x3d800000
	s_waitcnt lgkmcnt(0)
	v_lshlrev_b32_e32 v46, 16, v46
	v_lshlrev_b32_e32 v47, 16, v47
	v_lshlrev_b32_e32 v48, 16, v48
	v_lshlrev_b32_e32 v49, 16, v49
	v_lshlrev_b32_e32 v50, 16, v50
	v_lshlrev_b32_e32 v51, 16, v51
	v_lshlrev_b32_e32 v52, 16, v52
	v_lshlrev_b32_e32 v53, 16, v53
	v_lshlrev_b32_e32 v54, 16, v54
	v_lshlrev_b32_e32 v55, 16, v55
	v_lshlrev_b32_e32 v56, 16, v56
	v_lshlrev_b32_e32 v57, 16, v57
	v_lshlrev_b32_e32 v58, 16, v58
	v_lshlrev_b32_e32 v59, 16, v59
	v_lshlrev_b32_e32 v60, 16, v60
	v_lshlrev_b32_e32 v61, 16, v61
	v_lshlrev_b32_e32 v62, 16, v62
	v_lshlrev_b32_e32 v63, 16, v63
	v_lshlrev_b32_e32 v64, 16, v64
	v_lshlrev_b32_e32 v65, 16, v65
	v_lshlrev_b32_e32 v66, 16, v66
	v_lshlrev_b32_e32 v67, 16, v67
	v_lshlrev_b32_e32 v68, 16, v68
	v_lshlrev_b32_e32 v69, 16, v69
	v_lshlrev_b32_e32 v70, 16, v70
	v_lshlrev_b32_e32 v71, 16, v71
	v_lshlrev_b32_e32 v72, 16, v72
	v_lshlrev_b32_e32 v73, 16, v73
	v_lshlrev_b32_e32 v74, 16, v74
	v_lshlrev_b32_e32 v75, 16, v75
	v_lshlrev_b32_e32 v76, 16, v76
	v_lshlrev_b32_e32 v77, 16, v77
	v_lshlrev_b32_e32 v78, 16, v78
	v_lshlrev_b32_e32 v79, 16, v79
	v_lshlrev_b32_e32 v80, 16, v80
	v_lshlrev_b32_e32 v81, 16, v81
	v_lshlrev_b32_e32 v82, 16, v82
	v_lshlrev_b32_e32 v83, 16, v83
	v_lshlrev_b32_e32 v84, 16, v84
	v_lshlrev_b32_e32 v85, 16, v85
	v_lshlrev_b32_e32 v86, 16, v86
	v_lshlrev_b32_e32 v87, 16, v87
	v_lshlrev_b32_e32 v88, 16, v88
	v_lshlrev_b32_e32 v89, 16, v89
	v_lshlrev_b32_e32 v90, 16, v90
	v_lshlrev_b32_e32 v91, 16, v91
	v_lshlrev_b32_e32 v92, 16, v92
	s_cmp_eq_u32 s42, 1
	s_cbranch_scc0 .Lpool_nz3
	v_mov_b32_e32 v60, 0
	v_mov_b32_e32 v59, 0
	v_mov_b32_e32 v58, 0
	v_mov_b32_e32 v57, 0
	v_mov_b32_e32 v56, 0
	v_mov_b32_e32 v55, 0
	v_mov_b32_e32 v54, 0
	v_mov_b32_e32 v53, 0
	v_mov_b32_e32 v52, 0
	v_mov_b32_e32 v51, 0
	v_mov_b32_e32 v50, 0
	v_mov_b32_e32 v49, 0
	v_mov_b32_e32 v48, 0
	v_mov_b32_e32 v47, 0
	v_mov_b32_e32 v46, 0
.Lpool_nz3:
	v_add_f32_e32 v93, v61, v60
	v_add_f32_e32 v93, v93, v59
	v_add_f32_e32 v93, v93, v58
	v_add_f32_e32 v93, v93, v57
	v_add_f32_e32 v93, v93, v56
	v_add_f32_e32 v93, v93, v55
	v_add_f32_e32 v93, v93, v54
	v_add_f32_e32 v93, v93, v53
	v_add_f32_e32 v93, v93, v52
	v_add_f32_e32 v93, v93, v51
	v_add_f32_e32 v93, v93, v50
	v_add_f32_e32 v93, v93, v49
	v_add_f32_e32 v93, v93, v48
	v_add_f32_e32 v93, v93, v47
	v_add_f32_e32 v93, v93, v46
	s_cmp_eq_u32 s42, 1
	s_cselect_b32 s51, 0x3f800000, s50
	v_fma_f32 v2, v93, s51, -v61
	v_add_f32_e32 v93, v93, v62
	v_sub_f32_e32 v93, v93, v46
	s_cmp_eq_u32 s42, 1
	s_cselect_b32 s51, 0x3f000000, s50
	v_fma_f32 v3, v93, s51, -v62
	v_cvt_pk_bf16_f32 v2, v2, v3
	ds_write_b16 v9, v2 offset:0
	ds_write_b16_d16_hi v9, v2 offset:144
	v_add_f32_e32 v93, v93, v63
	v_sub_f32_e32 v93, v93, v47
	s_cmp_eq_u32 s42, 1
	s_cselect_b32 s51, 0x3eaaaaab, s50
	v_fma_f32 v4, v93, s51, -v63
	v_add_f32_e32 v93, v93, v64
	v_sub_f32_e32 v93, v93, v48
	s_cmp_eq_u32 s42, 1
	s_cselect_b32 s51, 0x3e800000, s50
	v_fma_f32 v5, v93, s51, -v64
	v_cvt_pk_bf16_f32 v4, v4, v5
	ds_write_b16 v9, v4 offset:288
	ds_write_b16_d16_hi v9, v4 offset:432
	v_add_f32_e32 v93, v93, v65
	v_sub_f32_e32 v93, v93, v49
	s_cmp_eq_u32 s42, 1
	s_cselect_b32 s51, 0x3e4ccccd, s50
	v_fma_f32 v2, v93, s51, -v65
	v_add_f32_e32 v93, v93, v66
	v_sub_f32_e32 v93, v93, v50
	s_cmp_eq_u32 s42, 1
	s_cselect_b32 s51, 0x3e2aaaab, s50
	v_fma_f32 v3, v93, s51, -v66
	v_cvt_pk_bf16_f32 v2, v2, v3
	ds_write_b16 v9, v2 offset:576
	ds_write_b16_d16_hi v9, v2 offset:720
	v_add_f32_e32 v93, v93, v67
	v_sub_f32_e32 v93, v93, v51
	s_cmp_eq_u32 s42, 1
	s_cselect_b32 s51, 0x3e124925, s50
	v_fma_f32 v4, v93, s51, -v67
	v_add_f32_e32 v93, v93, v68
	v_sub_f32_e32 v93, v93, v52
	s_cmp_eq_u32 s42, 1
	s_cselect_b32 s51, 0x3e000000, s50
	v_fma_f32 v5, v93, s51, -v68
	v_cvt_pk_bf16_f32 v4, v4, v5
	ds_write_b16 v9, v4 offset:864
	ds_write_b16_d16_hi v9, v4 offset:1008
	v_add_f32_e32 v93, v93, v69
	v_sub_f32_e32 v93, v93, v53
	s_cmp_eq_u32 s42, 1
	s_cselect_b32 s51, 0x3de38e39, s50
	v_fma_f32 v2, v93, s51, -v69
	v_add_f32_e32 v93, v93, v70
	v_sub_f32_e32 v93, v93, v54
	s_cmp_eq_u32 s42, 1
	s_cselect_b32 s51, 0x3dcccccd, s50
	v_fma_f32 v3, v93, s51, -v70
	v_cvt_pk_bf16_f32 v2, v2, v3
	ds_write_b16 v9, v2 offset:1152
	ds_write_b16_d16_hi v9, v2 offset:1296
	v_add_f32_e32 v93, v93, v71
	v_sub_f32_e32 v93, v93, v55
	s_cmp_eq_u32 s42, 1
	s_cselect_b32 s51, 0x3dba2e8c, s50
	v_fma_f32 v4, v93, s51, -v71
	v_add_f32_e32 v93, v93, v72
	v_sub_f32_e32 v93, v93, v56
	s_cmp_eq_u32 s42, 1
	s_cselect_b32 s51, 0x3daaaaab, s50
	v_fma_f32 v5, v93, s51, -v72
	v_cvt_pk_bf16_f32 v4, v4, v5
	ds_write_b16 v9, v4 offset:1440
	ds_write_b16_d16_hi v9, v4 offset:1584
	v_add_f32_e32 v93, v93, v73
	v_sub_f32_e32 v93, v93, v57
	s_cmp_eq_u32 s42, 1
	s_cselect_b32 s51, 0x3d9d89d9, s50
	v_fma_f32 v2, v93, s51, -v73
	v_add_f32_e32 v93, v93, v74
	v_sub_f32_e32 v93, v93, v58
	s_cmp_eq_u32 s42, 1
	s_cselect_b32 s51, 0x3d924925, s50
	v_fma_f32 v3, v93, s51, -v74
	v_cvt_pk_bf16_f32 v2, v2, v3
	ds_write_b16 v9, v2 offset:1728
	ds_write_b16_d16_hi v9, v2 offset:1872
	v_add_f32_e32 v93, v93, v75
	v_sub_f32_e32 v93, v93, v59
	s_cmp_eq_u32 s42, 1
	s_cselect_b32 s51, 0x3d888889, s50
	v_fma_f32 v4, v93, s51, -v75
	v_add_f32_e32 v93, v93, v76
	v_sub_f32_e32 v93, v93, v60
	v_fma_f32 v5, v93, s50, -v76
	v_cvt_pk_bf16_f32 v4, v4, v5
	ds_write_b16 v9, v4 offset:2016
	ds_write_b16_d16_hi v9, v4 offset:2160
	v_add_f32_e32 v93, v93, v77
	v_sub_f32_e32 v93, v93, v61
	v_fma_f32 v2, v93, s50, -v77
	v_add_f32_e32 v93, v93, v78
	v_sub_f32_e32 v93, v93, v62
	v_fma_f32 v3, v93, s50, -v78
	v_cvt_pk_bf16_f32 v2, v2, v3
	ds_write_b16 v9, v2 offset:2304
	ds_write_b16_d16_hi v9, v2 offset:2448
	v_add_f32_e32 v93, v93, v79
	v_sub_f32_e32 v93, v93, v63
	v_fma_f32 v4, v93, s50, -v79
	v_add_f32_e32 v93, v93, v80
	v_sub_f32_e32 v93, v93, v64
	v_fma_f32 v5, v93, s50, -v80
	v_cvt_pk_bf16_f32 v4, v4, v5
	ds_write_b16 v9, v4 offset:2592
	ds_write_b16_d16_hi v9, v4 offset:2736
	v_add_f32_e32 v93, v93, v81
	v_sub_f32_e32 v93, v93, v65
	v_fma_f32 v2, v93, s50, -v81
	v_add_f32_e32 v93, v93, v82
	v_sub_f32_e32 v93, v93, v66
	v_fma_f32 v3, v93, s50, -v82
	v_cvt_pk_bf16_f32 v2, v2, v3
	ds_write_b16 v9, v2 offset:2880
	ds_write_b16_d16_hi v9, v2 offset:3024
	v_add_f32_e32 v93, v93, v83
	v_sub_f32_e32 v93, v93, v67
	v_fma_f32 v4, v93, s50, -v83
	v_add_f32_e32 v93, v93, v84
	v_sub_f32_e32 v93, v93, v68
	v_fma_f32 v5, v93, s50, -v84
	v_cvt_pk_bf16_f32 v4, v4, v5
	ds_write_b16 v9, v4 offset:3168
	ds_write_b16_d16_hi v9, v4 offset:3312
	v_add_f32_e32 v93, v93, v85
	v_sub_f32_e32 v93, v93, v69
	v_fma_f32 v2, v93, s50, -v85
	v_add_f32_e32 v93, v93, v86
	v_sub_f32_e32 v93, v93, v70
	v_fma_f32 v3, v93, s50, -v86
	v_cvt_pk_bf16_f32 v2, v2, v3
	ds_write_b16 v9, v2 offset:3456
	ds_write_b16_d16_hi v9, v2 offset:3600
	v_add_f32_e32 v93, v93, v87
	v_sub_f32_e32 v93, v93, v71
	v_fma_f32 v4, v93, s50, -v87
	v_add_f32_e32 v93, v93, v88
	v_sub_f32_e32 v93, v93, v72
	v_fma_f32 v5, v93, s50, -v88
	v_cvt_pk_bf16_f32 v4, v4, v5
	ds_write_b16 v9, v4 offset:3744
	ds_write_b16_d16_hi v9, v4 offset:3888
	v_add_f32_e32 v93, v93, v89
	v_sub_f32_e32 v93, v93, v73
	v_fma_f32 v2, v93, s50, -v89
	v_add_f32_e32 v93, v93, v90
	v_sub_f32_e32 v93, v93, v74
	v_fma_f32 v3, v93, s50, -v90
	v_cvt_pk_bf16_f32 v2, v2, v3
	ds_write_b16 v9, v2 offset:4032
	ds_write_b16_d16_hi v9, v2 offset:4176
	v_add_f32_e32 v93, v93, v91
	v_sub_f32_e32 v93, v93, v75
	v_fma_f32 v4, v93, s50, -v91
	v_add_f32_e32 v93, v93, v92
	v_sub_f32_e32 v93, v93, v76
	v_fma_f32 v5, v93, s50, -v92
	v_cvt_pk_bf16_f32 v4, v4, v5
	ds_write_b16 v9, v4 offset:4320
	ds_write_b16_d16_hi v9, v4 offset:4464
	v_and_b32_e32 v2, 31, v0
	v_lshrrev_b32_e32 v3, 5, v0
	v_bfe_u32 v4, v0, 1, 3
	v_xor_b32_e32 v3, v3, v4
	v_lshlrev_b32_e32 v2, 7, v2
	v_add_u32_e32 v2, 0x1c000, v2
	v_lshl_add_u32 v5, v3, 4, v2
	v_xor_b32_e32 v4, 2, v3
	v_lshl_add_u32 v4, v4, 4, v2
	v_xor_b32_e32 v88, 4, v3
	v_xor_b32_e32 v3, 6, v3
	v_lshl_add_u32 v3, v3, 4, v2
	v_lshl_add_u32 v2, v88, 4, v2
	s_waitcnt lgkmcnt(0)
	ds_read_b128 v[28:31], v5 offset:0
	ds_read_b128 v[32:35], v5 offset:4096
	ds_read_b128 v[78:81], v44 offset:0
	ds_read_b128 v[82:85], v44 offset:32
	ds_read_b128 v[86:89], v44 offset:64
	ds_read_b128 v[90:93], v44 offset:96
	ds_read_b128 v[36:39], v4 offset:0
	ds_read_b128 v[40:43], v4 offset:4096
	s_waitcnt lgkmcnt(0)
	v_mfma_f32_32x32x16_bf16 v[46:61], v[28:31], v[78:81], 0
	v_mfma_f32_32x32x16_bf16 v[62:77], v[32:35], v[78:81], 0
	ds_read_b128 v[28:31], v2 offset:0
	ds_read_b128 v[32:35], v2 offset:4096
	v_mfma_f32_32x32x16_bf16 v[46:61], v[36:39], v[82:85], v[46:61]
	v_mfma_f32_32x32x16_bf16 v[62:77], v[40:43], v[82:85], v[62:77]
	ds_read_b128 v[36:39], v3 offset:0
	ds_read_b128 v[40:43], v3 offset:4096
	s_waitcnt lgkmcnt(2)
	v_mfma_f32_32x32x16_bf16 v[46:61], v[28:31], v[86:89], v[46:61]
	v_mfma_f32_32x32x16_bf16 v[62:77], v[32:35], v[86:89], v[62:77]
	s_waitcnt lgkmcnt(0)
	v_mfma_f32_32x32x16_bf16 v[46:61], v[36:39], v[90:93], v[46:61]
	v_mfma_f32_32x32x16_bf16 v[62:77], v[40:43], v[90:93], v[62:77]
	v_lshl_add_u64 v[4:5], s[52:53], 0, v[10:11]
	v_lshl_add_u64 v[98:99], s[52:53], 0, v[96:97]
	s_nop 14
	s_waitcnt vmcnt(0)
	s_mov_b32 s56, 0xbfb8aa3b
	s_mov_b32 s57, 0xbfb8aa3b
	s_mov_b32 s54, 1.0
	s_mov_b32 s55, 1.0
	v_lshlrev_b32_e32 v78, 16, v12
	v_and_b32_e32 v79, 0xffff0000, v12
	v_lshlrev_b32_e32 v80, 16, v13
	v_and_b32_e32 v81, 0xffff0000, v13
	v_lshlrev_b32_e32 v82, 16, v14
	v_and_b32_e32 v83, 0xffff0000, v14
	v_lshlrev_b32_e32 v84, 16, v15
	v_and_b32_e32 v85, 0xffff0000, v15
	v_lshlrev_b32_e32 v86, 16, v16
	v_and_b32_e32 v87, 0xffff0000, v16
	v_lshlrev_b32_e32 v88, 16, v17
	v_and_b32_e32 v89, 0xffff0000, v17
	v_lshlrev_b32_e32 v90, 16, v18
	v_and_b32_e32 v91, 0xffff0000, v18
	v_lshlrev_b32_e32 v92, 16, v19
	v_and_b32_e32 v93, 0xffff0000, v19
	v_pk_mul_f32 v[28:29], v[78:79], s[56:57]
	v_pk_mul_f32 v[30:31], v[80:81], s[56:57]
	v_pk_mul_f32 v[32:33], v[82:83], s[56:57]
	v_pk_mul_f32 v[34:35], v[84:85], s[56:57]
	v_pk_mul_f32 v[36:37], v[86:87], s[56:57]
	v_pk_mul_f32 v[38:39], v[88:89], s[56:57]
	v_pk_mul_f32 v[40:41], v[90:91], s[56:57]
	v_pk_mul_f32 v[42:43], v[92:93], s[56:57]
	v_exp_f32_e32 v28, v28
	v_exp_f32_e32 v29, v29
	v_exp_f32_e32 v30, v30
	v_exp_f32_e32 v31, v31
	v_exp_f32_e32 v32, v32
	v_exp_f32_e32 v33, v33
	v_exp_f32_e32 v34, v34
	v_exp_f32_e32 v35, v35
	v_exp_f32_e32 v36, v36
	v_exp_f32_e32 v37, v37
	v_exp_f32_e32 v38, v38
	v_exp_f32_e32 v39, v39
	v_exp_f32_e32 v40, v40
	v_exp_f32_e32 v41, v41
	v_exp_f32_e32 v42, v42
	v_exp_f32_e32 v43, v43
	v_pk_add_f32 v[28:29], v[28:29], s[54:55]
	v_pk_add_f32 v[30:31], v[30:31], s[54:55]
	v_pk_add_f32 v[32:33], v[32:33], s[54:55]
	v_pk_add_f32 v[34:35], v[34:35], s[54:55]
	v_pk_add_f32 v[36:37], v[36:37], s[54:55]
	v_pk_add_f32 v[38:39], v[38:39], s[54:55]
	v_pk_add_f32 v[40:41], v[40:41], s[54:55]
	v_pk_add_f32 v[42:43], v[42:43], s[54:55]
	v_rcp_f32_e32 v28, v28
	v_rcp_f32_e32 v29, v29
	v_rcp_f32_e32 v30, v30
	v_rcp_f32_e32 v31, v31
	v_rcp_f32_e32 v32, v32
	v_rcp_f32_e32 v33, v33
	v_rcp_f32_e32 v34, v34
	v_rcp_f32_e32 v35, v35
	v_rcp_f32_e32 v36, v36
	v_rcp_f32_e32 v37, v37
	v_rcp_f32_e32 v38, v38
	v_rcp_f32_e32 v39, v39
	v_rcp_f32_e32 v40, v40
	v_rcp_f32_e32 v41, v41
	v_rcp_f32_e32 v42, v42
	v_rcp_f32_e32 v43, v43
	v_pk_mul_f32 v[28:29], v[78:79], v[28:29]
	v_pk_mul_f32 v[30:31], v[80:81], v[30:31]
	v_pk_mul_f32 v[32:33], v[82:83], v[32:33]
	v_pk_mul_f32 v[34:35], v[84:85], v[34:35]
	v_pk_mul_f32 v[36:37], v[86:87], v[36:37]
	v_pk_mul_f32 v[38:39], v[88:89], v[38:39]
	v_pk_mul_f32 v[40:41], v[90:91], v[40:41]
	v_pk_mul_f32 v[42:43], v[92:93], v[42:43]
	v_pk_mul_f32 v[28:29], v[46:47], v[28:29]
	v_pk_mul_f32 v[30:31], v[48:49], v[30:31]
	v_pk_mul_f32 v[32:33], v[50:51], v[32:33]
	v_pk_mul_f32 v[34:35], v[52:53], v[34:35]
	v_pk_mul_f32 v[36:37], v[54:55], v[36:37]
	v_pk_mul_f32 v[38:39], v[56:57], v[38:39]
	v_pk_mul_f32 v[40:41], v[58:59], v[40:41]
	v_pk_mul_f32 v[42:43], v[60:61], v[42:43]
	v_cvt_pk_bf16_f32 v78, v28, v29
	v_cvt_pk_bf16_f32 v79, v30, v31
	v_cvt_pk_bf16_f32 v80, v32, v33
	v_cvt_pk_bf16_f32 v81, v34, v35
	v_cvt_pk_bf16_f32 v82, v36, v37
	v_cvt_pk_bf16_f32 v83, v38, v39
	v_cvt_pk_bf16_f32 v84, v40, v41
	v_cvt_pk_bf16_f32 v85, v42, v43
	s_nop 1
	v_permlane32_swap_b32 v78, v80
	v_permlane32_swap_b32 v79, v81
	v_permlane32_swap_b32 v82, v84
	v_permlane32_swap_b32 v83, v85
	global_store_dwordx4 v[98:99], v[78:81], off offset:384
	global_store_dwordx4 v[98:99], v[82:85], off offset:416
	s_nop 1
	v_lshlrev_b32_e32 v78, 16, v20
	v_and_b32_e32 v79, 0xffff0000, v20
	v_lshlrev_b32_e32 v80, 16, v21
	v_and_b32_e32 v81, 0xffff0000, v21
	v_lshlrev_b32_e32 v82, 16, v22
	v_and_b32_e32 v83, 0xffff0000, v22
	v_lshlrev_b32_e32 v84, 16, v23
	v_and_b32_e32 v85, 0xffff0000, v23
	v_lshlrev_b32_e32 v86, 16, v24
	v_and_b32_e32 v87, 0xffff0000, v24
	v_lshlrev_b32_e32 v88, 16, v25
	v_and_b32_e32 v89, 0xffff0000, v25
	v_lshlrev_b32_e32 v90, 16, v26
	v_and_b32_e32 v91, 0xffff0000, v26
	v_lshlrev_b32_e32 v92, 16, v27
	v_and_b32_e32 v93, 0xffff0000, v27
	v_pk_mul_f32 v[28:29], v[78:79], s[56:57]
	v_pk_mul_f32 v[30:31], v[80:81], s[56:57]
	v_pk_mul_f32 v[32:33], v[82:83], s[56:57]
	v_pk_mul_f32 v[34:35], v[84:85], s[56:57]
	v_pk_mul_f32 v[36:37], v[86:87], s[56:57]
	v_pk_mul_f32 v[38:39], v[88:89], s[56:57]
	v_pk_mul_f32 v[40:41], v[90:91], s[56:57]
	v_pk_mul_f32 v[42:43], v[92:93], s[56:57]
	v_exp_f32_e32 v28, v28
	v_exp_f32_e32 v29, v29
	v_exp_f32_e32 v30, v30
	v_exp_f32_e32 v31, v31
	v_exp_f32_e32 v32, v32
	v_exp_f32_e32 v33, v33
	v_exp_f32_e32 v34, v34
	v_exp_f32_e32 v35, v35
	v_exp_f32_e32 v36, v36
	v_exp_f32_e32 v37, v37
	v_exp_f32_e32 v38, v38
	v_exp_f32_e32 v39, v39
	v_exp_f32_e32 v40, v40
	v_exp_f32_e32 v41, v41
	v_exp_f32_e32 v42, v42
	v_exp_f32_e32 v43, v43
	v_pk_add_f32 v[28:29], v[28:29], s[54:55]
	v_pk_add_f32 v[30:31], v[30:31], s[54:55]
	v_pk_add_f32 v[32:33], v[32:33], s[54:55]
	v_pk_add_f32 v[34:35], v[34:35], s[54:55]
	v_pk_add_f32 v[36:37], v[36:37], s[54:55]
	v_pk_add_f32 v[38:39], v[38:39], s[54:55]
	v_pk_add_f32 v[40:41], v[40:41], s[54:55]
	v_pk_add_f32 v[42:43], v[42:43], s[54:55]
	v_rcp_f32_e32 v28, v28
	v_rcp_f32_e32 v29, v29
	v_rcp_f32_e32 v30, v30
	v_rcp_f32_e32 v31, v31
	v_rcp_f32_e32 v32, v32
	v_rcp_f32_e32 v33, v33
	v_rcp_f32_e32 v34, v34
	v_rcp_f32_e32 v35, v35
	v_rcp_f32_e32 v36, v36
	v_rcp_f32_e32 v37, v37
	v_rcp_f32_e32 v38, v38
	v_rcp_f32_e32 v39, v39
	v_rcp_f32_e32 v40, v40
	v_rcp_f32_e32 v41, v41
	v_rcp_f32_e32 v42, v42
	v_rcp_f32_e32 v43, v43
	v_pk_mul_f32 v[28:29], v[78:79], v[28:29]
	v_pk_mul_f32 v[30:31], v[80:81], v[30:31]
	v_pk_mul_f32 v[32:33], v[82:83], v[32:33]
	v_pk_mul_f32 v[34:35], v[84:85], v[34:35]
	v_pk_mul_f32 v[36:37], v[86:87], v[36:37]
	v_pk_mul_f32 v[38:39], v[88:89], v[38:39]
	v_pk_mul_f32 v[40:41], v[90:91], v[40:41]
	v_pk_mul_f32 v[42:43], v[92:93], v[42:43]
	v_pk_mul_f32 v[28:29], v[62:63], v[28:29]
	v_pk_mul_f32 v[30:31], v[64:65], v[30:31]
	v_pk_mul_f32 v[32:33], v[66:67], v[32:33]
	v_pk_mul_f32 v[34:35], v[68:69], v[34:35]
	v_pk_mul_f32 v[36:37], v[70:71], v[36:37]
	v_pk_mul_f32 v[38:39], v[72:73], v[38:39]
	v_pk_mul_f32 v[40:41], v[74:75], v[40:41]
	v_pk_mul_f32 v[42:43], v[76:77], v[42:43]
	v_cvt_pk_bf16_f32 v78, v28, v29
	v_cvt_pk_bf16_f32 v79, v30, v31
	v_cvt_pk_bf16_f32 v80, v32, v33
	v_cvt_pk_bf16_f32 v81, v34, v35
	v_cvt_pk_bf16_f32 v82, v36, v37
	v_cvt_pk_bf16_f32 v83, v38, v39
	v_cvt_pk_bf16_f32 v84, v40, v41
	v_cvt_pk_bf16_f32 v85, v42, v43
	s_nop 1
	v_permlane32_swap_b32 v78, v80
	v_permlane32_swap_b32 v79, v81
	v_permlane32_swap_b32 v82, v84
	v_permlane32_swap_b32 v83, v85
	global_store_dwordx4 v[98:99], v[78:81], off offset:448
	global_store_dwordx4 v[98:99], v[82:85], off offset:480
	s_waitcnt vmcnt(0)
	s_mov_b32 m0, s59
	v_readlane_b32 s38, v250, 39
	v_readlane_b32 s39, v250, 40
	s_barrier
